# pool item rewritten: row loads batched (1 round trip), window sums from registers, B/scale/gate loads all in flight
# speedup vs baseline: 1.1321x; 1.0357x over previous
; DI float bf2f(bfr b) { return __uint_as_float(((unsigned)b) << 16); }
; DI void pool_item(const Params& p, int layer, int isP, int sq, int tile, int g, char*) {
;     ...
;   {
;     const int c = tid & 127;
; #pragma unroll
;     for (int b8 = 0; b8 < 5; ++b8) {
;       float vv[8];
; #pragma unroll
;       for (int u = 0; u < 8; ++u) {
;         const int rr = (b8 * 8 + u) * 2 + (tid >> 7);
;         const int tt = t0 - 15 + rr;
;         float v = 0.f;
;         if (rr < 79) {
;           if (tt < 0) { if (!isP) v = p.state_pool[((long)(layer * NB_S + sq) * 15 + (15 + tt)) * 512 + ch0 + c]; }
;           else if (tt < T) v = bf2f(xcb[(long)(rowbase + tt) * 512 + ch0 + c]);
;         }
;         vv[u] = v;
;       }
; #pragma unroll
;       for (int u = 0; u < 8; ++u) { const int rr = (b8 * 8 + u) * 2 + (tid >> 7); if (rr < 79) xps[rr * 128 + c] = vv[u]; }
;     }
;   }
.LBB0_2392:
	s_and_b64 vcc, exec, s[0:1]
	s_cbranch_vccz .LBB0_2623
	s_add_i32 s0, s60, 0xf39c
	s_and_b32 s1, s0, 0xffff
	s_mulk_i32 s1, 0xfc1
	s_lshr_b32 s16, s1, 20
	s_mul_i32 s1, s16, 0x104
	s_sub_i32 s0, s0, s1
	s_and_b32 s1, s0, 0xffff
	s_and_b32 s19, s0, 3
	s_lshl_b32 s0, s1, 4
	s_and_b32 s17, s0, 0x1fc0
	v_mov_b32_e32 v2, v158
	s_add_i32 s20, s17, -15
	s_lshl_b32 s0, s19, 8
	v_readlane_b32 s1, v251, 53
	s_add_u32 s0, s1, s0
	s_waitcnt vmcnt(0)
	v_and_b32_e32 v4, 0x7f, v2
	v_readlane_b32 s1, v251, 54
	v_ashrrev_i32_e32 v3, 7, v2
	s_addc_u32 s1, s1, 0
	v_lshlrev_b32_e32 v128, 1, v4
	v_lshl_add_u64 v[0:1], s[0:1], 0, v[128:129]
	v_readfirstlane_b32 s18, v2
	s_mulk_i32 s16, 0x1010
	v_lshl_add_u32 v5, v4, 2, v169
	s_lshr_b32 s22, s18, 7
	s_add_i32 s21, s20, s22
	s_add_i32 s2, s21, s16
	s_ashr_i32 s3, s2, 31
	s_lshl_b64 s[2:3], s[2:3], 10
	v_mov_b32_e32 v7, s3
	v_add_co_u32_e32 v8, vcc, s2, v0
	s_nop 1
	v_addc_co_u32_e32 v9, vcc, v7, v1, vcc
	v_lshl_add_u32 v6, v3, 9, v5
	v_mov_b32_e32 v52, 0
	v_mov_b32_e32 v53, 0
	v_mov_b32_e32 v54, 0
	v_mov_b32_e32 v55, 0
	v_mov_b32_e32 v56, 0
	v_mov_b32_e32 v57, 0
	v_mov_b32_e32 v58, 0
	v_mov_b32_e32 v59, 0
	v_mov_b32_e32 v60, 0
	v_mov_b32_e32 v61, 0
	v_mov_b32_e32 v62, 0
	v_mov_b32_e32 v63, 0
	v_mov_b32_e32 v64, 0
	v_mov_b32_e32 v65, 0
	v_mov_b32_e32 v66, 0
	v_mov_b32_e32 v67, 0
	v_mov_b32_e32 v68, 0
	v_mov_b32_e32 v69, 0
	v_mov_b32_e32 v70, 0
	v_mov_b32_e32 v71, 0
	v_mov_b32_e32 v72, 0
	v_mov_b32_e32 v73, 0
	v_mov_b32_e32 v74, 0
	v_mov_b32_e32 v75, 0
	v_mov_b32_e32 v76, 0
	v_mov_b32_e32 v77, 0
	v_mov_b32_e32 v78, 0
	v_mov_b32_e32 v79, 0
	v_mov_b32_e32 v80, 0
	v_mov_b32_e32 v81, 0
	v_mov_b32_e32 v82, 0
	v_mov_b32_e32 v83, 0
	v_mov_b32_e32 v84, 0
	v_mov_b32_e32 v85, 0
	v_mov_b32_e32 v86, 0
	v_mov_b32_e32 v87, 0
	v_mov_b32_e32 v88, 0
	v_mov_b32_e32 v89, 0
	v_mov_b32_e32 v90, 0
	v_mov_b32_e32 v91, 0
	s_cmp_lt_u32 s21, s92
	s_cbranch_scc0 .Lpl1_n0
	global_load_ushort v52, v[8:9], off
.Lpl1_n0:
	s_add_i32 s21, s21, 2
	s_cmp_lt_u32 s21, s92
	s_cbranch_scc0 .Lpl1_n1
	global_load_ushort v53, v[8:9], off offset:2048
.Lpl1_n1:
	s_add_i32 s21, s21, 2
	v_add_co_u32_e32 v8, vcc, 0x1000, v8
	s_nop 1
	v_addc_co_u32_e32 v9, vcc, 0, v9, vcc
	s_cmp_lt_u32 s21, s92
	s_cbranch_scc0 .Lpl1_n2
	global_load_ushort v54, v[8:9], off
.Lpl1_n2:
	s_add_i32 s21, s21, 2
	s_cmp_lt_u32 s21, s92
	s_cbranch_scc0 .Lpl1_n3
	global_load_ushort v55, v[8:9], off offset:2048
.Lpl1_n3:
	s_add_i32 s21, s21, 2
	v_add_co_u32_e32 v8, vcc, 0x1000, v8
	s_nop 1
	v_addc_co_u32_e32 v9, vcc, 0, v9, vcc
	s_cmp_lt_u32 s21, s92
	s_cbranch_scc0 .Lpl1_n4
	global_load_ushort v56, v[8:9], off
.Lpl1_n4:
	s_add_i32 s21, s21, 2
	s_cmp_lt_u32 s21, s92
	s_cbranch_scc0 .Lpl1_n5
	global_load_ushort v57, v[8:9], off offset:2048
.Lpl1_n5:
	s_add_i32 s21, s21, 2
	v_add_co_u32_e32 v8, vcc, 0x1000, v8
	s_nop 1
	v_addc_co_u32_e32 v9, vcc, 0, v9, vcc
	s_cmp_lt_u32 s21, s92
	s_cbranch_scc0 .Lpl1_n6
	global_load_ushort v58, v[8:9], off
.Lpl1_n6:
	s_add_i32 s21, s21, 2
	s_cmp_lt_u32 s21, s92
	s_cbranch_scc0 .Lpl1_n7
	global_load_ushort v59, v[8:9], off offset:2048
.Lpl1_n7:
	s_add_i32 s21, s21, 2
	v_add_co_u32_e32 v8, vcc, 0x1000, v8
	s_nop 1
	v_addc_co_u32_e32 v9, vcc, 0, v9, vcc
	s_cmp_lt_u32 s21, s92
	s_cbranch_scc0 .Lpl1_n8
	global_load_ushort v60, v[8:9], off
.Lpl1_n8:
	s_add_i32 s21, s21, 2
	s_cmp_lt_u32 s21, s92
	s_cbranch_scc0 .Lpl1_n9
	global_load_ushort v61, v[8:9], off offset:2048
.Lpl1_n9:
	s_add_i32 s21, s21, 2
	v_add_co_u32_e32 v8, vcc, 0x1000, v8
	s_nop 1
	v_addc_co_u32_e32 v9, vcc, 0, v9, vcc
	s_cmp_lt_u32 s21, s92
	s_cbranch_scc0 .Lpl1_n10
	global_load_ushort v62, v[8:9], off
.Lpl1_n10:
	s_add_i32 s21, s21, 2
	s_cmp_lt_u32 s21, s92
	s_cbranch_scc0 .Lpl1_n11
	global_load_ushort v63, v[8:9], off offset:2048
.Lpl1_n11:
	s_add_i32 s21, s21, 2
	v_add_co_u32_e32 v8, vcc, 0x1000, v8
	s_nop 1
	v_addc_co_u32_e32 v9, vcc, 0, v9, vcc
	s_cmp_lt_u32 s21, s92
	s_cbranch_scc0 .Lpl1_n12
	global_load_ushort v64, v[8:9], off
.Lpl1_n12:
	s_add_i32 s21, s21, 2
	s_cmp_lt_u32 s21, s92
	s_cbranch_scc0 .Lpl1_n13
	global_load_ushort v65, v[8:9], off offset:2048
.Lpl1_n13:
	s_add_i32 s21, s21, 2
	v_add_co_u32_e32 v8, vcc, 0x1000, v8
	s_nop 1
	v_addc_co_u32_e32 v9, vcc, 0, v9, vcc
	s_cmp_lt_u32 s21, s92
	s_cbranch_scc0 .Lpl1_n14
	global_load_ushort v66, v[8:9], off
.Lpl1_n14:
	s_add_i32 s21, s21, 2
	s_cmp_lt_u32 s21, s92
	s_cbranch_scc0 .Lpl1_n15
	global_load_ushort v67, v[8:9], off offset:2048
.Lpl1_n15:
	s_add_i32 s21, s21, 2
	v_add_co_u32_e32 v8, vcc, 0x1000, v8
	s_nop 1
	v_addc_co_u32_e32 v9, vcc, 0, v9, vcc
	s_cmp_lt_u32 s21, s92
	s_cbranch_scc0 .Lpl1_n16
	global_load_ushort v68, v[8:9], off
.Lpl1_n16:
	s_add_i32 s21, s21, 2
	s_cmp_lt_u32 s21, s92
	s_cbranch_scc0 .Lpl1_n17
	global_load_ushort v69, v[8:9], off offset:2048
.Lpl1_n17:
	s_add_i32 s21, s21, 2
	v_add_co_u32_e32 v8, vcc, 0x1000, v8
	s_nop 1
	v_addc_co_u32_e32 v9, vcc, 0, v9, vcc
	s_cmp_lt_u32 s21, s92
	s_cbranch_scc0 .Lpl1_n18
	global_load_ushort v70, v[8:9], off
.Lpl1_n18:
	s_add_i32 s21, s21, 2
	s_cmp_lt_u32 s21, s92
	s_cbranch_scc0 .Lpl1_n19
	global_load_ushort v71, v[8:9], off offset:2048
.Lpl1_n19:
	s_add_i32 s21, s21, 2
	v_add_co_u32_e32 v8, vcc, 0x1000, v8
	s_nop 1
	v_addc_co_u32_e32 v9, vcc, 0, v9, vcc
	s_cmp_lt_u32 s21, s92
	s_cbranch_scc0 .Lpl1_n20
	global_load_ushort v72, v[8:9], off
.Lpl1_n20:
	s_add_i32 s21, s21, 2
	s_cmp_lt_u32 s21, s92
	s_cbranch_scc0 .Lpl1_n21
	global_load_ushort v73, v[8:9], off offset:2048
.Lpl1_n21:
	s_add_i32 s21, s21, 2
	v_add_co_u32_e32 v8, vcc, 0x1000, v8
	s_nop 1
	v_addc_co_u32_e32 v9, vcc, 0, v9, vcc
	s_cmp_lt_u32 s21, s92
	s_cbranch_scc0 .Lpl1_n22
	global_load_ushort v74, v[8:9], off
; DI float bf2f(bfr b) { return __uint_as_float(((unsigned)b) << 16); }
; DI void pool_item(const Params& p, int layer, int isP, int sq, int tile, int g, char*) {
;     ...
;   {
;     const int c = tid & 127;
; #pragma unroll
;     for (int b8 = 0; b8 < 5; ++b8) {
;       float vv[8];
; #pragma unroll
;       for (int u = 0; u < 8; ++u) {
;         const int rr = (b8 * 8 + u) * 2 + (tid >> 7);
;         const int tt = t0 - 15 + rr;
;         float v = 0.f;
;         if (rr < 79) {
;           if (tt < 0) { if (!isP) v = p.state_pool[((long)(layer * NB_S + sq) * 15 + (15 + tt)) * 512 + ch0 + c]; }
;           else if (tt < T) v = bf2f(xcb[(long)(rowbase + tt) * 512 + ch0 + c]);
;         }
;         vv[u] = v;
;       }
; #pragma unroll
;       for (int u = 0; u < 8; ++u) { const int rr = (b8 * 8 + u) * 2 + (tid >> 7); if (rr < 79) xps[rr * 128 + c] = vv[u]; }
;     }
;   }
.Lpl1_n22:
	s_add_i32 s21, s21, 2
	s_cmp_lt_u32 s21, s92
	s_cbranch_scc0 .Lpl1_n23
	global_load_ushort v75, v[8:9], off offset:2048
.Lpl1_n23:
	s_add_i32 s21, s21, 2
	v_add_co_u32_e32 v8, vcc, 0x1000, v8
	s_nop 1
	v_addc_co_u32_e32 v9, vcc, 0, v9, vcc
	s_cmp_lt_u32 s21, s92
	s_cbranch_scc0 .Lpl1_n24
	global_load_ushort v76, v[8:9], off
.Lpl1_n24:
	s_add_i32 s21, s21, 2
	s_cmp_lt_u32 s21, s92
	s_cbranch_scc0 .Lpl1_n25
	global_load_ushort v77, v[8:9], off offset:2048
.Lpl1_n25:
	s_add_i32 s21, s21, 2
	v_add_co_u32_e32 v8, vcc, 0x1000, v8
	s_nop 1
	v_addc_co_u32_e32 v9, vcc, 0, v9, vcc
	s_cmp_lt_u32 s21, s92
	s_cbranch_scc0 .Lpl1_n26
	global_load_ushort v78, v[8:9], off
.Lpl1_n26:
	s_add_i32 s21, s21, 2
	s_cmp_lt_u32 s21, s92
	s_cbranch_scc0 .Lpl1_n27
	global_load_ushort v79, v[8:9], off offset:2048
.Lpl1_n27:
	s_add_i32 s21, s21, 2
	v_add_co_u32_e32 v8, vcc, 0x1000, v8
	s_nop 1
	v_addc_co_u32_e32 v9, vcc, 0, v9, vcc
	s_cmp_lt_u32 s21, s92
	s_cbranch_scc0 .Lpl1_n28
	global_load_ushort v80, v[8:9], off
.Lpl1_n28:
	s_add_i32 s21, s21, 2
	s_cmp_lt_u32 s21, s92
	s_cbranch_scc0 .Lpl1_n29
	global_load_ushort v81, v[8:9], off offset:2048
.Lpl1_n29:
	s_add_i32 s21, s21, 2
	v_add_co_u32_e32 v8, vcc, 0x1000, v8
	s_nop 1
	v_addc_co_u32_e32 v9, vcc, 0, v9, vcc
	s_cmp_lt_u32 s21, s92
	s_cbranch_scc0 .Lpl1_n30
	global_load_ushort v82, v[8:9], off
.Lpl1_n30:
	s_add_i32 s21, s21, 2
	s_cmp_lt_u32 s21, s92
	s_cbranch_scc0 .Lpl1_n31
	global_load_ushort v83, v[8:9], off offset:2048
.Lpl1_n31:
	s_add_i32 s21, s21, 2
	v_add_co_u32_e32 v8, vcc, 0x1000, v8
	s_nop 1
	v_addc_co_u32_e32 v9, vcc, 0, v9, vcc
	s_cmp_lt_u32 s21, s92
	s_cbranch_scc0 .Lpl1_n32
	global_load_ushort v84, v[8:9], off
.Lpl1_n32:
	s_add_i32 s21, s21, 2
	s_cmp_lt_u32 s21, s92
	s_cbranch_scc0 .Lpl1_n33
	global_load_ushort v85, v[8:9], off offset:2048
.Lpl1_n33:
	s_add_i32 s21, s21, 2
	v_add_co_u32_e32 v8, vcc, 0x1000, v8
	s_nop 1
	v_addc_co_u32_e32 v9, vcc, 0, v9, vcc
	s_cmp_lt_u32 s21, s92
	s_cbranch_scc0 .Lpl1_n34
	global_load_ushort v86, v[8:9], off
.Lpl1_n34:
	s_add_i32 s21, s21, 2
	s_cmp_lt_u32 s21, s92
	s_cbranch_scc0 .Lpl1_n35
	global_load_ushort v87, v[8:9], off offset:2048
.Lpl1_n35:
	s_add_i32 s21, s21, 2
	v_add_co_u32_e32 v8, vcc, 0x1000, v8
	s_nop 1
	v_addc_co_u32_e32 v9, vcc, 0, v9, vcc
	s_cmp_lt_u32 s21, s92
	s_cbranch_scc0 .Lpl1_n36
	global_load_ushort v88, v[8:9], off
.Lpl1_n36:
	s_add_i32 s21, s21, 2
	s_cmp_lt_u32 s21, s92
	s_cbranch_scc0 .Lpl1_n37
	global_load_ushort v89, v[8:9], off offset:2048
.Lpl1_n37:
	s_add_i32 s21, s21, 2
	v_add_co_u32_e32 v8, vcc, 0x1000, v8
	s_nop 1
	v_addc_co_u32_e32 v9, vcc, 0, v9, vcc
	s_cmp_lt_u32 s21, s92
	s_cbranch_scc0 .Lpl1_n38
	global_load_ushort v90, v[8:9], off
.Lpl1_n38:
	s_add_i32 s21, s21, 2
	s_cmp_lt_u32 s21, s92
	s_cbranch_scc0 .Lpl1_n39
	global_load_ushort v91, v[8:9], off offset:2048
.Lpl1_n39:
	s_add_i32 s21, s21, 2
	s_waitcnt vmcnt(0)
	v_lshlrev_b32_e32 v52, 16, v52
	ds_write_b32 v6, v52
	v_lshlrev_b32_e32 v53, 16, v53
	ds_write_b32 v6, v53 offset:1024
	v_lshlrev_b32_e32 v54, 16, v54
	ds_write_b32 v6, v54 offset:2048
	v_lshlrev_b32_e32 v55, 16, v55
	ds_write_b32 v6, v55 offset:3072
	v_lshlrev_b32_e32 v56, 16, v56
	ds_write_b32 v6, v56 offset:4096
	v_lshlrev_b32_e32 v57, 16, v57
	ds_write_b32 v6, v57 offset:5120
	v_lshlrev_b32_e32 v58, 16, v58
	ds_write_b32 v6, v58 offset:6144
	v_lshlrev_b32_e32 v59, 16, v59
	ds_write_b32 v6, v59 offset:7168
	v_lshlrev_b32_e32 v60, 16, v60
	ds_write_b32 v6, v60 offset:8192
	v_lshlrev_b32_e32 v61, 16, v61
	ds_write_b32 v6, v61 offset:9216
	v_lshlrev_b32_e32 v62, 16, v62
	ds_write_b32 v6, v62 offset:10240
	v_lshlrev_b32_e32 v63, 16, v63
	ds_write_b32 v6, v63 offset:11264
	v_lshlrev_b32_e32 v64, 16, v64
	ds_write_b32 v6, v64 offset:12288
	v_lshlrev_b32_e32 v65, 16, v65
	ds_write_b32 v6, v65 offset:13312
	v_lshlrev_b32_e32 v66, 16, v66
	ds_write_b32 v6, v66 offset:14336
	v_lshlrev_b32_e32 v67, 16, v67
	ds_write_b32 v6, v67 offset:15360
	v_lshlrev_b32_e32 v68, 16, v68
	ds_write_b32 v6, v68 offset:16384
	v_lshlrev_b32_e32 v69, 16, v69
	ds_write_b32 v6, v69 offset:17408
	v_lshlrev_b32_e32 v70, 16, v70
	ds_write_b32 v6, v70 offset:18432
	v_lshlrev_b32_e32 v71, 16, v71
	ds_write_b32 v6, v71 offset:19456
	v_lshlrev_b32_e32 v72, 16, v72
	ds_write_b32 v6, v72 offset:20480
	v_lshlrev_b32_e32 v73, 16, v73
	ds_write_b32 v6, v73 offset:21504
	v_lshlrev_b32_e32 v74, 16, v74
	ds_write_b32 v6, v74 offset:22528
	v_lshlrev_b32_e32 v75, 16, v75
	ds_write_b32 v6, v75 offset:23552
	v_lshlrev_b32_e32 v76, 16, v76
	ds_write_b32 v6, v76 offset:24576
	v_lshlrev_b32_e32 v77, 16, v77
	ds_write_b32 v6, v77 offset:25600
	v_lshlrev_b32_e32 v78, 16, v78
	ds_write_b32 v6, v78 offset:26624
	v_lshlrev_b32_e32 v79, 16, v79
	ds_write_b32 v6, v79 offset:27648
	v_lshlrev_b32_e32 v80, 16, v80
	ds_write_b32 v6, v80 offset:28672
	v_lshlrev_b32_e32 v81, 16, v81
	ds_write_b32 v6, v81 offset:29696
	v_lshlrev_b32_e32 v82, 16, v82
	ds_write_b32 v6, v82 offset:30720
	v_lshlrev_b32_e32 v83, 16, v83
	ds_write_b32 v6, v83 offset:31744
	v_lshlrev_b32_e32 v84, 16, v84
	ds_write_b32 v6, v84 offset:32768
	v_lshlrev_b32_e32 v85, 16, v85
	ds_write_b32 v6, v85 offset:33792
	v_lshlrev_b32_e32 v86, 16, v86
	ds_write_b32 v6, v86 offset:34816
	v_lshlrev_b32_e32 v87, 16, v87
	ds_write_b32 v6, v87 offset:35840
	v_lshlrev_b32_e32 v88, 16, v88
	ds_write_b32 v6, v88 offset:36864
	v_lshlrev_b32_e32 v89, 16, v89
	ds_write_b32 v6, v89 offset:37888
	v_lshlrev_b32_e32 v90, 16, v90
	ds_write_b32 v6, v90 offset:38912
	s_cmp_lg_u32 s22, 0
	s_cbranch_scc1 .Lpl1_done
	v_lshlrev_b32_e32 v91, 16, v91
	ds_write_b32 v6, v91 offset:39936
.Lpl1_done:
	s_mov_b64 s[0:1], -1
; DI bfr f2bf(float x) { return (bfr)(pack2(x, 0.f) & 0xFFFFu); }
; DI void pool_item(const Params& p, int layer, int isP, int sq, int tile, int g, char*) {
;     ...
;   {
;     const int c = tid & 127;
;     const int w = 2 << g;
;     const int nh = isP ? 0 : PAST;
;     for (int t = tid >> 7; t < 64; t += 2) {
;       float s = 0.f;
;       for (int i = 0; i < w; ++i) s += xps[(15 + t - i) * 128 + c];
;       int cnt = min(w, t0 + t + 1 + nh);
;       float v = s / (float)cnt - xps[(15 + t) * 128 + c];
;       pa[t * 136 + c] = f2bf(v);
;     }
;   }
.LBB0_2513:
	s_or_b64 exec, exec, s[0:1]
	v_cmp_gt_i32_e32 vcc, 64, v3
	s_waitcnt lgkmcnt(0)
	s_barrier
	s_and_saveexec_b64 s[0:1], vcc
	s_cbranch_execz .LBB0_2518
	s_cmp_eq_u32 s17, 0
	s_cbranch_scc1 .Lpl2_slow
	v_lshl_add_u32 v6, v3, 9, v5
	v_lshl_add_u32 v7, v4, 1, v169
	v_mul_u32_u24_e32 v8, 0x110, v3
	v_add_u32_e32 v7, v7, v8
	ds_read2st64_b32 v[52:53], v6 offset0:0 offset1:2
	ds_read2st64_b32 v[54:55], v6 offset0:4 offset1:6
	ds_read2st64_b32 v[56:57], v6 offset0:8 offset1:10
	ds_read2st64_b32 v[58:59], v6 offset0:12 offset1:14
	ds_read2st64_b32 v[60:61], v6 offset0:16 offset1:18
	ds_read2st64_b32 v[62:63], v6 offset0:20 offset1:22
	ds_read2st64_b32 v[64:65], v6 offset0:24 offset1:26
	ds_read2st64_b32 v[66:67], v6 offset0:28 offset1:30
	ds_read2st64_b32 v[68:69], v6 offset0:32 offset1:34
	ds_read2st64_b32 v[70:71], v6 offset0:36 offset1:38
	ds_read2st64_b32 v[72:73], v6 offset0:40 offset1:42
	ds_read2st64_b32 v[74:75], v6 offset0:44 offset1:46
	ds_read2st64_b32 v[76:77], v6 offset0:48 offset1:50
	ds_read2st64_b32 v[78:79], v6 offset0:52 offset1:54
	ds_read2st64_b32 v[80:81], v6 offset0:56 offset1:58
	ds_read2st64_b32 v[82:83], v6 offset0:60 offset1:62
	ds_read2st64_b32 v[84:85], v6 offset0:64 offset1:66
	ds_read2st64_b32 v[86:87], v6 offset0:68 offset1:70
	ds_read2st64_b32 v[88:89], v6 offset0:72 offset1:74
	ds_read2st64_b32 v[90:91], v6 offset0:76 offset1:78
	ds_read2st64_b32 v[92:93], v6 offset0:80 offset1:82
	ds_read2st64_b32 v[94:95], v6 offset0:84 offset1:86
	ds_read2st64_b32 v[96:97], v6 offset0:88 offset1:90
	ds_read2st64_b32 v[98:99], v6 offset0:92 offset1:94
	ds_read2st64_b32 v[100:101], v6 offset0:96 offset1:98
	ds_read2st64_b32 v[102:103], v6 offset0:100 offset1:102
	ds_read2st64_b32 v[104:105], v6 offset0:104 offset1:106
	ds_read2st64_b32 v[106:107], v6 offset0:108 offset1:110
	ds_read2st64_b32 v[108:109], v6 offset0:112 offset1:114
	ds_read2st64_b32 v[110:111], v6 offset0:116 offset1:118
	ds_read2st64_b32 v[112:113], v6 offset0:120 offset1:122
	ds_read2st64_b32 v[114:115], v6 offset0:124 offset1:126
	ds_read2st64_b32 v[116:117], v6 offset0:128 offset1:130
	ds_read2st64_b32 v[118:119], v6 offset0:132 offset1:134
	ds_read2st64_b32 v[120:121], v6 offset0:136 offset1:138
	ds_read2st64_b32 v[122:123], v6 offset0:140 offset1:142
	ds_read2st64_b32 v[124:125], v6 offset0:144 offset1:146
	ds_read2st64_b32 v[126:127], v6 offset0:148 offset1:150
	ds_read2st64_b32 v[132:133], v6 offset0:152 offset1:154
	s_waitcnt lgkmcnt(0)
	s_cmp_eq_u32 s19, 0
	s_cbranch_scc1 .Lpl2_w2
	s_cmp_eq_u32 s19, 1
	s_cbranch_scc1 .Lpl2_w4
	s_cmp_eq_u32 s19, 2
	s_cbranch_scc1 .Lpl2_w8
	v_add_f32_e32 v9, 0, v67
	v_add_f32_e32 v9, v9, v66
	v_add_f32_e32 v9, v9, v65
	v_add_f32_e32 v9, v9, v64
	v_add_f32_e32 v9, v9, v63
	v_add_f32_e32 v9, v9, v62
	v_add_f32_e32 v9, v9, v61
	v_add_f32_e32 v9, v9, v60
	v_add_f32_e32 v9, v9, v59
	v_add_f32_e32 v9, v9, v58
	v_add_f32_e32 v9, v9, v57
	v_add_f32_e32 v9, v9, v56
	v_add_f32_e32 v9, v9, v55
	v_add_f32_e32 v9, v9, v54
	v_add_f32_e32 v9, v9, v53
	v_add_f32_e32 v9, v9, v52
	v_mul_f32_e32 v9, 0x3d800000, v9
	v_sub_f32_e32 v9, v9, v67
	v_cvt_pk_bf16_f32 v9, v9, v9
	ds_write_b16 v7, v9 offset:40448
	v_add_f32_e32 v9, 0, v69
	v_add_f32_e32 v9, v9, v68
	v_add_f32_e32 v9, v9, v67
	v_add_f32_e32 v9, v9, v66
	v_add_f32_e32 v9, v9, v65
	v_add_f32_e32 v9, v9, v64
	v_add_f32_e32 v9, v9, v63
	v_add_f32_e32 v9, v9, v62
	v_add_f32_e32 v9, v9, v61
	v_add_f32_e32 v9, v9, v60
	v_add_f32_e32 v9, v9, v59
	v_add_f32_e32 v9, v9, v58
	v_add_f32_e32 v9, v9, v57
	v_add_f32_e32 v9, v9, v56
	v_add_f32_e32 v9, v9, v55
	v_add_f32_e32 v9, v9, v54
	v_mul_f32_e32 v9, 0x3d800000, v9
	v_sub_f32_e32 v9, v9, v69
	v_cvt_pk_bf16_f32 v9, v9, v9
	ds_write_b16 v7, v9 offset:40992
	v_add_f32_e32 v9, 0, v71
	v_add_f32_e32 v9, v9, v70
	v_add_f32_e32 v9, v9, v69
	v_add_f32_e32 v9, v9, v68
	v_add_f32_e32 v9, v9, v67
	v_add_f32_e32 v9, v9, v66
	v_add_f32_e32 v9, v9, v65
	v_add_f32_e32 v9, v9, v64
	v_add_f32_e32 v9, v9, v63
	v_add_f32_e32 v9, v9, v62
	v_add_f32_e32 v9, v9, v61
	v_add_f32_e32 v9, v9, v60
	v_add_f32_e32 v9, v9, v59
	v_add_f32_e32 v9, v9, v58
	v_add_f32_e32 v9, v9, v57
	v_add_f32_e32 v9, v9, v56
	v_mul_f32_e32 v9, 0x3d800000, v9
	v_sub_f32_e32 v9, v9, v71
	v_cvt_pk_bf16_f32 v9, v9, v9
	ds_write_b16 v7, v9 offset:41536
	v_add_f32_e32 v9, 0, v73
	v_add_f32_e32 v9, v9, v72
	v_add_f32_e32 v9, v9, v71
	v_add_f32_e32 v9, v9, v70
	v_add_f32_e32 v9, v9, v69
	v_add_f32_e32 v9, v9, v68
	v_add_f32_e32 v9, v9, v67
	v_add_f32_e32 v9, v9, v66
	v_add_f32_e32 v9, v9, v65
	v_add_f32_e32 v9, v9, v64
	v_add_f32_e32 v9, v9, v63
	v_add_f32_e32 v9, v9, v62
	v_add_f32_e32 v9, v9, v61
	v_add_f32_e32 v9, v9, v60
	v_add_f32_e32 v9, v9, v59
	v_add_f32_e32 v9, v9, v58
	v_mul_f32_e32 v9, 0x3d800000, v9
	v_sub_f32_e32 v9, v9, v73
	v_cvt_pk_bf16_f32 v9, v9, v9
	ds_write_b16 v7, v9 offset:42080
	v_add_f32_e32 v9, 0, v75
	v_add_f32_e32 v9, v9, v74
	v_add_f32_e32 v9, v9, v73
	v_add_f32_e32 v9, v9, v72
	v_add_f32_e32 v9, v9, v71
	v_add_f32_e32 v9, v9, v70
	v_add_f32_e32 v9, v9, v69
	v_add_f32_e32 v9, v9, v68
	v_add_f32_e32 v9, v9, v67
	v_add_f32_e32 v9, v9, v66
	v_add_f32_e32 v9, v9, v65
	v_add_f32_e32 v9, v9, v64
	v_add_f32_e32 v9, v9, v63
	v_add_f32_e32 v9, v9, v62
	v_add_f32_e32 v9, v9, v61
	v_add_f32_e32 v9, v9, v60
	v_mul_f32_e32 v9, 0x3d800000, v9
	v_sub_f32_e32 v9, v9, v75
	v_cvt_pk_bf16_f32 v9, v9, v9
	ds_write_b16 v7, v9 offset:42624
	v_add_f32_e32 v9, 0, v77
	v_add_f32_e32 v9, v9, v76
	v_add_f32_e32 v9, v9, v75
	v_add_f32_e32 v9, v9, v74
	v_add_f32_e32 v9, v9, v73
	v_add_f32_e32 v9, v9, v72
	v_add_f32_e32 v9, v9, v71
	v_add_f32_e32 v9, v9, v70
	v_add_f32_e32 v9, v9, v69
; DI bfr f2bf(float x) { return (bfr)(pack2(x, 0.f) & 0xFFFFu); }
; DI void pool_item(const Params& p, int layer, int isP, int sq, int tile, int g, char*) {
;     ...
;   {
;     const int c = tid & 127;
;     const int w = 2 << g;
;     const int nh = isP ? 0 : PAST;
;     for (int t = tid >> 7; t < 64; t += 2) {
;       float s = 0.f;
;       for (int i = 0; i < w; ++i) s += xps[(15 + t - i) * 128 + c];
;       int cnt = min(w, t0 + t + 1 + nh);
;       float v = s / (float)cnt - xps[(15 + t) * 128 + c];
;       pa[t * 136 + c] = f2bf(v);
;     }
;   }
	v_add_f32_e32 v9, v9, v68
	v_add_f32_e32 v9, v9, v67
	v_add_f32_e32 v9, v9, v66
	v_add_f32_e32 v9, v9, v65
	v_add_f32_e32 v9, v9, v64
	v_add_f32_e32 v9, v9, v63
	v_add_f32_e32 v9, v9, v62
	v_mul_f32_e32 v9, 0x3d800000, v9
	v_sub_f32_e32 v9, v9, v77
	v_cvt_pk_bf16_f32 v9, v9, v9
	ds_write_b16 v7, v9 offset:43168
	v_add_f32_e32 v9, 0, v79
	v_add_f32_e32 v9, v9, v78
	v_add_f32_e32 v9, v9, v77
	v_add_f32_e32 v9, v9, v76
	v_add_f32_e32 v9, v9, v75
	v_add_f32_e32 v9, v9, v74
	v_add_f32_e32 v9, v9, v73
	v_add_f32_e32 v9, v9, v72
	v_add_f32_e32 v9, v9, v71
	v_add_f32_e32 v9, v9, v70
	v_add_f32_e32 v9, v9, v69
	v_add_f32_e32 v9, v9, v68
	v_add_f32_e32 v9, v9, v67
	v_add_f32_e32 v9, v9, v66
	v_add_f32_e32 v9, v9, v65
	v_add_f32_e32 v9, v9, v64
	v_mul_f32_e32 v9, 0x3d800000, v9
	v_sub_f32_e32 v9, v9, v79
	v_cvt_pk_bf16_f32 v9, v9, v9
	ds_write_b16 v7, v9 offset:43712
	v_add_f32_e32 v9, 0, v81
	v_add_f32_e32 v9, v9, v80
	v_add_f32_e32 v9, v9, v79
	v_add_f32_e32 v9, v9, v78
	v_add_f32_e32 v9, v9, v77
	v_add_f32_e32 v9, v9, v76
	v_add_f32_e32 v9, v9, v75
	v_add_f32_e32 v9, v9, v74
	v_add_f32_e32 v9, v9, v73
	v_add_f32_e32 v9, v9, v72
	v_add_f32_e32 v9, v9, v71
	v_add_f32_e32 v9, v9, v70
	v_add_f32_e32 v9, v9, v69
	v_add_f32_e32 v9, v9, v68
	v_add_f32_e32 v9, v9, v67
	v_add_f32_e32 v9, v9, v66
	v_mul_f32_e32 v9, 0x3d800000, v9
	v_sub_f32_e32 v9, v9, v81
	v_cvt_pk_bf16_f32 v9, v9, v9
	ds_write_b16 v7, v9 offset:44256
	v_add_f32_e32 v9, 0, v83
	v_add_f32_e32 v9, v9, v82
	v_add_f32_e32 v9, v9, v81
	v_add_f32_e32 v9, v9, v80
	v_add_f32_e32 v9, v9, v79
	v_add_f32_e32 v9, v9, v78
	v_add_f32_e32 v9, v9, v77
	v_add_f32_e32 v9, v9, v76
	v_add_f32_e32 v9, v9, v75
	v_add_f32_e32 v9, v9, v74
	v_add_f32_e32 v9, v9, v73
	v_add_f32_e32 v9, v9, v72
	v_add_f32_e32 v9, v9, v71
	v_add_f32_e32 v9, v9, v70
	v_add_f32_e32 v9, v9, v69
	v_add_f32_e32 v9, v9, v68
	v_mul_f32_e32 v9, 0x3d800000, v9
	v_sub_f32_e32 v9, v9, v83
	v_cvt_pk_bf16_f32 v9, v9, v9
	ds_write_b16 v7, v9 offset:44800
	v_add_f32_e32 v9, 0, v85
	v_add_f32_e32 v9, v9, v84
	v_add_f32_e32 v9, v9, v83
	v_add_f32_e32 v9, v9, v82
	v_add_f32_e32 v9, v9, v81
	v_add_f32_e32 v9, v9, v80
	v_add_f32_e32 v9, v9, v79
	v_add_f32_e32 v9, v9, v78
	v_add_f32_e32 v9, v9, v77
	v_add_f32_e32 v9, v9, v76
	v_add_f32_e32 v9, v9, v75
	v_add_f32_e32 v9, v9, v74
	v_add_f32_e32 v9, v9, v73
	v_add_f32_e32 v9, v9, v72
	v_add_f32_e32 v9, v9, v71
	v_add_f32_e32 v9, v9, v70
	v_mul_f32_e32 v9, 0x3d800000, v9
	v_sub_f32_e32 v9, v9, v85
	v_cvt_pk_bf16_f32 v9, v9, v9
	ds_write_b16 v7, v9 offset:45344
	v_add_f32_e32 v9, 0, v87
	v_add_f32_e32 v9, v9, v86
	v_add_f32_e32 v9, v9, v85
	v_add_f32_e32 v9, v9, v84
	v_add_f32_e32 v9, v9, v83
	v_add_f32_e32 v9, v9, v82
	v_add_f32_e32 v9, v9, v81
	v_add_f32_e32 v9, v9, v80
	v_add_f32_e32 v9, v9, v79
	v_add_f32_e32 v9, v9, v78
	v_add_f32_e32 v9, v9, v77
	v_add_f32_e32 v9, v9, v76
	v_add_f32_e32 v9, v9, v75
	v_add_f32_e32 v9, v9, v74
	v_add_f32_e32 v9, v9, v73
	v_add_f32_e32 v9, v9, v72
	v_mul_f32_e32 v9, 0x3d800000, v9
	v_sub_f32_e32 v9, v9, v87
	v_cvt_pk_bf16_f32 v9, v9, v9
	ds_write_b16 v7, v9 offset:45888
	v_add_f32_e32 v9, 0, v89
	v_add_f32_e32 v9, v9, v88
	v_add_f32_e32 v9, v9, v87
	v_add_f32_e32 v9, v9, v86
	v_add_f32_e32 v9, v9, v85
	v_add_f32_e32 v9, v9, v84
	v_add_f32_e32 v9, v9, v83
	v_add_f32_e32 v9, v9, v82
	v_add_f32_e32 v9, v9, v81
	v_add_f32_e32 v9, v9, v80
	v_add_f32_e32 v9, v9, v79
	v_add_f32_e32 v9, v9, v78
	v_add_f32_e32 v9, v9, v77
	v_add_f32_e32 v9, v9, v76
	v_add_f32_e32 v9, v9, v75
	v_add_f32_e32 v9, v9, v74
	v_mul_f32_e32 v9, 0x3d800000, v9
	v_sub_f32_e32 v9, v9, v89
	v_cvt_pk_bf16_f32 v9, v9, v9
	ds_write_b16 v7, v9 offset:46432
	v_add_f32_e32 v9, 0, v91
	v_add_f32_e32 v9, v9, v90
	v_add_f32_e32 v9, v9, v89
	v_add_f32_e32 v9, v9, v88
	v_add_f32_e32 v9, v9, v87
	v_add_f32_e32 v9, v9, v86
	v_add_f32_e32 v9, v9, v85
	v_add_f32_e32 v9, v9, v84
	v_add_f32_e32 v9, v9, v83
	v_add_f32_e32 v9, v9, v82
	v_add_f32_e32 v9, v9, v81
	v_add_f32_e32 v9, v9, v80
	v_add_f32_e32 v9, v9, v79
	v_add_f32_e32 v9, v9, v78
	v_add_f32_e32 v9, v9, v77
	v_add_f32_e32 v9, v9, v76
	v_mul_f32_e32 v9, 0x3d800000, v9
	v_sub_f32_e32 v9, v9, v91
	v_cvt_pk_bf16_f32 v9, v9, v9
	ds_write_b16 v7, v9 offset:46976
	v_add_f32_e32 v9, 0, v93
	v_add_f32_e32 v9, v9, v92
	v_add_f32_e32 v9, v9, v91
	v_add_f32_e32 v9, v9, v90
	v_add_f32_e32 v9, v9, v89
	v_add_f32_e32 v9, v9, v88
	v_add_f32_e32 v9, v9, v87
	v_add_f32_e32 v9, v9, v86
	v_add_f32_e32 v9, v9, v85
	v_add_f32_e32 v9, v9, v84
	v_add_f32_e32 v9, v9, v83
	v_add_f32_e32 v9, v9, v82
	v_add_f32_e32 v9, v9, v81
	v_add_f32_e32 v9, v9, v80
	v_add_f32_e32 v9, v9, v79
	v_add_f32_e32 v9, v9, v78
	v_mul_f32_e32 v9, 0x3d800000, v9
	v_sub_f32_e32 v9, v9, v93
	v_cvt_pk_bf16_f32 v9, v9, v9
	ds_write_b16 v7, v9 offset:47520
	v_add_f32_e32 v9, 0, v95
	v_add_f32_e32 v9, v9, v94
	v_add_f32_e32 v9, v9, v93
	v_add_f32_e32 v9, v9, v92
	v_add_f32_e32 v9, v9, v91
	v_add_f32_e32 v9, v9, v90
	v_add_f32_e32 v9, v9, v89
	v_add_f32_e32 v9, v9, v88
	v_add_f32_e32 v9, v9, v87
	v_add_f32_e32 v9, v9, v86
	v_add_f32_e32 v9, v9, v85
	v_add_f32_e32 v9, v9, v84
	v_add_f32_e32 v9, v9, v83
	v_add_f32_e32 v9, v9, v82
	v_add_f32_e32 v9, v9, v81
	v_add_f32_e32 v9, v9, v80
	v_mul_f32_e32 v9, 0x3d800000, v9
	v_sub_f32_e32 v9, v9, v95
	v_cvt_pk_bf16_f32 v9, v9, v9
	ds_write_b16 v7, v9 offset:48064
	v_add_f32_e32 v9, 0, v97
	v_add_f32_e32 v9, v9, v96
	v_add_f32_e32 v9, v9, v95
	v_add_f32_e32 v9, v9, v94
	v_add_f32_e32 v9, v9, v93
	v_add_f32_e32 v9, v9, v92
	v_add_f32_e32 v9, v9, v91
	v_add_f32_e32 v9, v9, v90
	v_add_f32_e32 v9, v9, v89
	v_add_f32_e32 v9, v9, v88
	v_add_f32_e32 v9, v9, v87
	v_add_f32_e32 v9, v9, v86
; DI bfr f2bf(float x) { return (bfr)(pack2(x, 0.f) & 0xFFFFu); }
; DI void pool_item(const Params& p, int layer, int isP, int sq, int tile, int g, char*) {
;     ...
;   {
;     const int c = tid & 127;
;     const int w = 2 << g;
;     const int nh = isP ? 0 : PAST;
;     for (int t = tid >> 7; t < 64; t += 2) {
;       float s = 0.f;
;       for (int i = 0; i < w; ++i) s += xps[(15 + t - i) * 128 + c];
;       int cnt = min(w, t0 + t + 1 + nh);
;       float v = s / (float)cnt - xps[(15 + t) * 128 + c];
;       pa[t * 136 + c] = f2bf(v);
;     }
;   }
	v_add_f32_e32 v9, v9, v85
	v_add_f32_e32 v9, v9, v84
	v_add_f32_e32 v9, v9, v83
	v_add_f32_e32 v9, v9, v82
	v_mul_f32_e32 v9, 0x3d800000, v9
	v_sub_f32_e32 v9, v9, v97
	v_cvt_pk_bf16_f32 v9, v9, v9
	ds_write_b16 v7, v9 offset:48608
	v_add_f32_e32 v9, 0, v99
	v_add_f32_e32 v9, v9, v98
	v_add_f32_e32 v9, v9, v97
	v_add_f32_e32 v9, v9, v96
	v_add_f32_e32 v9, v9, v95
	v_add_f32_e32 v9, v9, v94
	v_add_f32_e32 v9, v9, v93
	v_add_f32_e32 v9, v9, v92
	v_add_f32_e32 v9, v9, v91
	v_add_f32_e32 v9, v9, v90
	v_add_f32_e32 v9, v9, v89
	v_add_f32_e32 v9, v9, v88
	v_add_f32_e32 v9, v9, v87
	v_add_f32_e32 v9, v9, v86
	v_add_f32_e32 v9, v9, v85
	v_add_f32_e32 v9, v9, v84
	v_mul_f32_e32 v9, 0x3d800000, v9
	v_sub_f32_e32 v9, v9, v99
	v_cvt_pk_bf16_f32 v9, v9, v9
	ds_write_b16 v7, v9 offset:49152
	v_add_f32_e32 v9, 0, v101
	v_add_f32_e32 v9, v9, v100
	v_add_f32_e32 v9, v9, v99
	v_add_f32_e32 v9, v9, v98
	v_add_f32_e32 v9, v9, v97
	v_add_f32_e32 v9, v9, v96
	v_add_f32_e32 v9, v9, v95
	v_add_f32_e32 v9, v9, v94
	v_add_f32_e32 v9, v9, v93
	v_add_f32_e32 v9, v9, v92
	v_add_f32_e32 v9, v9, v91
	v_add_f32_e32 v9, v9, v90
	v_add_f32_e32 v9, v9, v89
	v_add_f32_e32 v9, v9, v88
	v_add_f32_e32 v9, v9, v87
	v_add_f32_e32 v9, v9, v86
	v_mul_f32_e32 v9, 0x3d800000, v9
	v_sub_f32_e32 v9, v9, v101
	v_cvt_pk_bf16_f32 v9, v9, v9
	ds_write_b16 v7, v9 offset:49696
	v_add_f32_e32 v9, 0, v103
	v_add_f32_e32 v9, v9, v102
	v_add_f32_e32 v9, v9, v101
	v_add_f32_e32 v9, v9, v100
	v_add_f32_e32 v9, v9, v99
	v_add_f32_e32 v9, v9, v98
	v_add_f32_e32 v9, v9, v97
	v_add_f32_e32 v9, v9, v96
	v_add_f32_e32 v9, v9, v95
	v_add_f32_e32 v9, v9, v94
	v_add_f32_e32 v9, v9, v93
	v_add_f32_e32 v9, v9, v92
	v_add_f32_e32 v9, v9, v91
	v_add_f32_e32 v9, v9, v90
	v_add_f32_e32 v9, v9, v89
	v_add_f32_e32 v9, v9, v88
	v_mul_f32_e32 v9, 0x3d800000, v9
	v_sub_f32_e32 v9, v9, v103
	v_cvt_pk_bf16_f32 v9, v9, v9
	ds_write_b16 v7, v9 offset:50240
	v_add_f32_e32 v9, 0, v105
	v_add_f32_e32 v9, v9, v104
	v_add_f32_e32 v9, v9, v103
	v_add_f32_e32 v9, v9, v102
	v_add_f32_e32 v9, v9, v101
	v_add_f32_e32 v9, v9, v100
	v_add_f32_e32 v9, v9, v99
	v_add_f32_e32 v9, v9, v98
	v_add_f32_e32 v9, v9, v97
	v_add_f32_e32 v9, v9, v96
	v_add_f32_e32 v9, v9, v95
	v_add_f32_e32 v9, v9, v94
	v_add_f32_e32 v9, v9, v93
	v_add_f32_e32 v9, v9, v92
	v_add_f32_e32 v9, v9, v91
	v_add_f32_e32 v9, v9, v90
	v_mul_f32_e32 v9, 0x3d800000, v9
	v_sub_f32_e32 v9, v9, v105
	v_cvt_pk_bf16_f32 v9, v9, v9
	ds_write_b16 v7, v9 offset:50784
	v_add_f32_e32 v9, 0, v107
	v_add_f32_e32 v9, v9, v106
	v_add_f32_e32 v9, v9, v105
	v_add_f32_e32 v9, v9, v104
	v_add_f32_e32 v9, v9, v103
	v_add_f32_e32 v9, v9, v102
	v_add_f32_e32 v9, v9, v101
	v_add_f32_e32 v9, v9, v100
	v_add_f32_e32 v9, v9, v99
	v_add_f32_e32 v9, v9, v98
	v_add_f32_e32 v9, v9, v97
	v_add_f32_e32 v9, v9, v96
	v_add_f32_e32 v9, v9, v95
	v_add_f32_e32 v9, v9, v94
	v_add_f32_e32 v9, v9, v93
	v_add_f32_e32 v9, v9, v92
	v_mul_f32_e32 v9, 0x3d800000, v9
	v_sub_f32_e32 v9, v9, v107
	v_cvt_pk_bf16_f32 v9, v9, v9
	ds_write_b16 v7, v9 offset:51328
	v_add_f32_e32 v9, 0, v109
	v_add_f32_e32 v9, v9, v108
	v_add_f32_e32 v9, v9, v107
	v_add_f32_e32 v9, v9, v106
	v_add_f32_e32 v9, v9, v105
	v_add_f32_e32 v9, v9, v104
	v_add_f32_e32 v9, v9, v103
	v_add_f32_e32 v9, v9, v102
	v_add_f32_e32 v9, v9, v101
	v_add_f32_e32 v9, v9, v100
	v_add_f32_e32 v9, v9, v99
	v_add_f32_e32 v9, v9, v98
	v_add_f32_e32 v9, v9, v97
	v_add_f32_e32 v9, v9, v96
	v_add_f32_e32 v9, v9, v95
	v_add_f32_e32 v9, v9, v94
	v_mul_f32_e32 v9, 0x3d800000, v9
	v_sub_f32_e32 v9, v9, v109
	v_cvt_pk_bf16_f32 v9, v9, v9
	ds_write_b16 v7, v9 offset:51872
	v_add_f32_e32 v9, 0, v111
	v_add_f32_e32 v9, v9, v110
	v_add_f32_e32 v9, v9, v109
	v_add_f32_e32 v9, v9, v108
	v_add_f32_e32 v9, v9, v107
	v_add_f32_e32 v9, v9, v106
	v_add_f32_e32 v9, v9, v105
	v_add_f32_e32 v9, v9, v104
	v_add_f32_e32 v9, v9, v103
	v_add_f32_e32 v9, v9, v102
	v_add_f32_e32 v9, v9, v101
	v_add_f32_e32 v9, v9, v100
	v_add_f32_e32 v9, v9, v99
	v_add_f32_e32 v9, v9, v98
	v_add_f32_e32 v9, v9, v97
	v_add_f32_e32 v9, v9, v96
	v_mul_f32_e32 v9, 0x3d800000, v9
	v_sub_f32_e32 v9, v9, v111
	v_cvt_pk_bf16_f32 v9, v9, v9
	ds_write_b16 v7, v9 offset:52416
	v_add_f32_e32 v9, 0, v113
	v_add_f32_e32 v9, v9, v112
	v_add_f32_e32 v9, v9, v111
	v_add_f32_e32 v9, v9, v110
	v_add_f32_e32 v9, v9, v109
	v_add_f32_e32 v9, v9, v108
	v_add_f32_e32 v9, v9, v107
	v_add_f32_e32 v9, v9, v106
	v_add_f32_e32 v9, v9, v105
	v_add_f32_e32 v9, v9, v104
	v_add_f32_e32 v9, v9, v103
	v_add_f32_e32 v9, v9, v102
	v_add_f32_e32 v9, v9, v101
	v_add_f32_e32 v9, v9, v100
	v_add_f32_e32 v9, v9, v99
	v_add_f32_e32 v9, v9, v98
	v_mul_f32_e32 v9, 0x3d800000, v9
	v_sub_f32_e32 v9, v9, v113
	v_cvt_pk_bf16_f32 v9, v9, v9
	ds_write_b16 v7, v9 offset:52960
	v_add_f32_e32 v9, 0, v115
	v_add_f32_e32 v9, v9, v114
	v_add_f32_e32 v9, v9, v113
	v_add_f32_e32 v9, v9, v112
	v_add_f32_e32 v9, v9, v111
	v_add_f32_e32 v9, v9, v110
	v_add_f32_e32 v9, v9, v109
	v_add_f32_e32 v9, v9, v108
	v_add_f32_e32 v9, v9, v107
	v_add_f32_e32 v9, v9, v106
	v_add_f32_e32 v9, v9, v105
	v_add_f32_e32 v9, v9, v104
	v_add_f32_e32 v9, v9, v103
	v_add_f32_e32 v9, v9, v102
	v_add_f32_e32 v9, v9, v101
	v_add_f32_e32 v9, v9, v100
	v_mul_f32_e32 v9, 0x3d800000, v9
	v_sub_f32_e32 v9, v9, v115
	v_cvt_pk_bf16_f32 v9, v9, v9
	ds_write_b16 v7, v9 offset:53504
	v_add_f32_e32 v9, 0, v117
	v_add_f32_e32 v9, v9, v116
	v_add_f32_e32 v9, v9, v115
	v_add_f32_e32 v9, v9, v114
	v_add_f32_e32 v9, v9, v113
	v_add_f32_e32 v9, v9, v112
	v_add_f32_e32 v9, v9, v111
	v_add_f32_e32 v9, v9, v110
	v_add_f32_e32 v9, v9, v109
	v_add_f32_e32 v9, v9, v108
	v_add_f32_e32 v9, v9, v107
	v_add_f32_e32 v9, v9, v106
; DI bfr f2bf(float x) { return (bfr)(pack2(x, 0.f) & 0xFFFFu); }
; DI void pool_item(const Params& p, int layer, int isP, int sq, int tile, int g, char*) {
;     ...
;   {
;     const int c = tid & 127;
;     const int w = 2 << g;
;     const int nh = isP ? 0 : PAST;
;     for (int t = tid >> 7; t < 64; t += 2) {
;       float s = 0.f;
;       for (int i = 0; i < w; ++i) s += xps[(15 + t - i) * 128 + c];
;       int cnt = min(w, t0 + t + 1 + nh);
;       float v = s / (float)cnt - xps[(15 + t) * 128 + c];
;       pa[t * 136 + c] = f2bf(v);
;     }
;   }
	v_add_f32_e32 v9, v9, v105
	v_add_f32_e32 v9, v9, v104
	v_add_f32_e32 v9, v9, v103
	v_add_f32_e32 v9, v9, v102
	v_mul_f32_e32 v9, 0x3d800000, v9
	v_sub_f32_e32 v9, v9, v117
	v_cvt_pk_bf16_f32 v9, v9, v9
	ds_write_b16 v7, v9 offset:54048
	v_add_f32_e32 v9, 0, v119
	v_add_f32_e32 v9, v9, v118
	v_add_f32_e32 v9, v9, v117
	v_add_f32_e32 v9, v9, v116
	v_add_f32_e32 v9, v9, v115
	v_add_f32_e32 v9, v9, v114
	v_add_f32_e32 v9, v9, v113
	v_add_f32_e32 v9, v9, v112
	v_add_f32_e32 v9, v9, v111
	v_add_f32_e32 v9, v9, v110
	v_add_f32_e32 v9, v9, v109
	v_add_f32_e32 v9, v9, v108
	v_add_f32_e32 v9, v9, v107
	v_add_f32_e32 v9, v9, v106
	v_add_f32_e32 v9, v9, v105
	v_add_f32_e32 v9, v9, v104
	v_mul_f32_e32 v9, 0x3d800000, v9
	v_sub_f32_e32 v9, v9, v119
	v_cvt_pk_bf16_f32 v9, v9, v9
	ds_write_b16 v7, v9 offset:54592
	v_add_f32_e32 v9, 0, v121
	v_add_f32_e32 v9, v9, v120
	v_add_f32_e32 v9, v9, v119
	v_add_f32_e32 v9, v9, v118
	v_add_f32_e32 v9, v9, v117
	v_add_f32_e32 v9, v9, v116
	v_add_f32_e32 v9, v9, v115
	v_add_f32_e32 v9, v9, v114
	v_add_f32_e32 v9, v9, v113
	v_add_f32_e32 v9, v9, v112
	v_add_f32_e32 v9, v9, v111
	v_add_f32_e32 v9, v9, v110
	v_add_f32_e32 v9, v9, v109
	v_add_f32_e32 v9, v9, v108
	v_add_f32_e32 v9, v9, v107
	v_add_f32_e32 v9, v9, v106
	v_mul_f32_e32 v9, 0x3d800000, v9
	v_sub_f32_e32 v9, v9, v121
	v_cvt_pk_bf16_f32 v9, v9, v9
	ds_write_b16 v7, v9 offset:55136
	v_add_f32_e32 v9, 0, v123
	v_add_f32_e32 v9, v9, v122
	v_add_f32_e32 v9, v9, v121
	v_add_f32_e32 v9, v9, v120
	v_add_f32_e32 v9, v9, v119
	v_add_f32_e32 v9, v9, v118
	v_add_f32_e32 v9, v9, v117
	v_add_f32_e32 v9, v9, v116
	v_add_f32_e32 v9, v9, v115
	v_add_f32_e32 v9, v9, v114
	v_add_f32_e32 v9, v9, v113
	v_add_f32_e32 v9, v9, v112
	v_add_f32_e32 v9, v9, v111
	v_add_f32_e32 v9, v9, v110
	v_add_f32_e32 v9, v9, v109
	v_add_f32_e32 v9, v9, v108
	v_mul_f32_e32 v9, 0x3d800000, v9
	v_sub_f32_e32 v9, v9, v123
	v_cvt_pk_bf16_f32 v9, v9, v9
	ds_write_b16 v7, v9 offset:55680
	v_add_f32_e32 v9, 0, v125
	v_add_f32_e32 v9, v9, v124
	v_add_f32_e32 v9, v9, v123
	v_add_f32_e32 v9, v9, v122
	v_add_f32_e32 v9, v9, v121
	v_add_f32_e32 v9, v9, v120
	v_add_f32_e32 v9, v9, v119
	v_add_f32_e32 v9, v9, v118
	v_add_f32_e32 v9, v9, v117
	v_add_f32_e32 v9, v9, v116
	v_add_f32_e32 v9, v9, v115
	v_add_f32_e32 v9, v9, v114
	v_add_f32_e32 v9, v9, v113
	v_add_f32_e32 v9, v9, v112
	v_add_f32_e32 v9, v9, v111
	v_add_f32_e32 v9, v9, v110
	v_mul_f32_e32 v9, 0x3d800000, v9
	v_sub_f32_e32 v9, v9, v125
	v_cvt_pk_bf16_f32 v9, v9, v9
	ds_write_b16 v7, v9 offset:56224
	v_add_f32_e32 v9, 0, v127
	v_add_f32_e32 v9, v9, v126
	v_add_f32_e32 v9, v9, v125
	v_add_f32_e32 v9, v9, v124
	v_add_f32_e32 v9, v9, v123
	v_add_f32_e32 v9, v9, v122
	v_add_f32_e32 v9, v9, v121
	v_add_f32_e32 v9, v9, v120
	v_add_f32_e32 v9, v9, v119
	v_add_f32_e32 v9, v9, v118
	v_add_f32_e32 v9, v9, v117
	v_add_f32_e32 v9, v9, v116
	v_add_f32_e32 v9, v9, v115
	v_add_f32_e32 v9, v9, v114
	v_add_f32_e32 v9, v9, v113
	v_add_f32_e32 v9, v9, v112
	v_mul_f32_e32 v9, 0x3d800000, v9
	v_sub_f32_e32 v9, v9, v127
	v_cvt_pk_bf16_f32 v9, v9, v9
	ds_write_b16 v7, v9 offset:56768
	v_add_f32_e32 v9, 0, v133
	v_add_f32_e32 v9, v9, v132
	v_add_f32_e32 v9, v9, v127
	v_add_f32_e32 v9, v9, v126
	v_add_f32_e32 v9, v9, v125
	v_add_f32_e32 v9, v9, v124
	v_add_f32_e32 v9, v9, v123
	v_add_f32_e32 v9, v9, v122
	v_add_f32_e32 v9, v9, v121
	v_add_f32_e32 v9, v9, v120
	v_add_f32_e32 v9, v9, v119
	v_add_f32_e32 v9, v9, v118
	v_add_f32_e32 v9, v9, v117
	v_add_f32_e32 v9, v9, v116
	v_add_f32_e32 v9, v9, v115
	v_add_f32_e32 v9, v9, v114
	v_mul_f32_e32 v9, 0x3d800000, v9
	v_sub_f32_e32 v9, v9, v133
	v_cvt_pk_bf16_f32 v9, v9, v9
	ds_write_b16 v7, v9 offset:57312
	s_mov_b64 s[0:1], -1
	s_branch .LBB0_2518
.Lpl2_w2:
	v_add_f32_e32 v9, 0, v67
	v_add_f32_e32 v9, v9, v66
	v_mul_f32_e32 v9, 0.5, v9
	v_sub_f32_e32 v9, v9, v67
	v_cvt_pk_bf16_f32 v9, v9, v9
	ds_write_b16 v7, v9 offset:40448
	v_add_f32_e32 v9, 0, v69
	v_add_f32_e32 v9, v9, v68
	v_mul_f32_e32 v9, 0.5, v9
	v_sub_f32_e32 v9, v9, v69
	v_cvt_pk_bf16_f32 v9, v9, v9
	ds_write_b16 v7, v9 offset:40992
	v_add_f32_e32 v9, 0, v71
	v_add_f32_e32 v9, v9, v70
	v_mul_f32_e32 v9, 0.5, v9
	v_sub_f32_e32 v9, v9, v71
	v_cvt_pk_bf16_f32 v9, v9, v9
	ds_write_b16 v7, v9 offset:41536
	v_add_f32_e32 v9, 0, v73
	v_add_f32_e32 v9, v9, v72
	v_mul_f32_e32 v9, 0.5, v9
	v_sub_f32_e32 v9, v9, v73
	v_cvt_pk_bf16_f32 v9, v9, v9
	ds_write_b16 v7, v9 offset:42080
	v_add_f32_e32 v9, 0, v75
	v_add_f32_e32 v9, v9, v74
	v_mul_f32_e32 v9, 0.5, v9
	v_sub_f32_e32 v9, v9, v75
	v_cvt_pk_bf16_f32 v9, v9, v9
	ds_write_b16 v7, v9 offset:42624
	v_add_f32_e32 v9, 0, v77
	v_add_f32_e32 v9, v9, v76
	v_mul_f32_e32 v9, 0.5, v9
	v_sub_f32_e32 v9, v9, v77
	v_cvt_pk_bf16_f32 v9, v9, v9
	ds_write_b16 v7, v9 offset:43168
	v_add_f32_e32 v9, 0, v79
	v_add_f32_e32 v9, v9, v78
	v_mul_f32_e32 v9, 0.5, v9
	v_sub_f32_e32 v9, v9, v79
	v_cvt_pk_bf16_f32 v9, v9, v9
	ds_write_b16 v7, v9 offset:43712
	v_add_f32_e32 v9, 0, v81
	v_add_f32_e32 v9, v9, v80
	v_mul_f32_e32 v9, 0.5, v9
	v_sub_f32_e32 v9, v9, v81
	v_cvt_pk_bf16_f32 v9, v9, v9
	ds_write_b16 v7, v9 offset:44256
	v_add_f32_e32 v9, 0, v83
	v_add_f32_e32 v9, v9, v82
	v_mul_f32_e32 v9, 0.5, v9
	v_sub_f32_e32 v9, v9, v83
	v_cvt_pk_bf16_f32 v9, v9, v9
	ds_write_b16 v7, v9 offset:44800
	v_add_f32_e32 v9, 0, v85
	v_add_f32_e32 v9, v9, v84
	v_mul_f32_e32 v9, 0.5, v9
	v_sub_f32_e32 v9, v9, v85
	v_cvt_pk_bf16_f32 v9, v9, v9
	ds_write_b16 v7, v9 offset:45344
	v_add_f32_e32 v9, 0, v87
	v_add_f32_e32 v9, v9, v86
	v_mul_f32_e32 v9, 0.5, v9
	v_sub_f32_e32 v9, v9, v87
	v_cvt_pk_bf16_f32 v9, v9, v9
	ds_write_b16 v7, v9 offset:45888
	v_add_f32_e32 v9, 0, v89
; DI bfr f2bf(float x) { return (bfr)(pack2(x, 0.f) & 0xFFFFu); }
; DI void pool_item(const Params& p, int layer, int isP, int sq, int tile, int g, char*) {
;     ...
;   {
;     const int c = tid & 127;
;     const int w = 2 << g;
;     const int nh = isP ? 0 : PAST;
;     for (int t = tid >> 7; t < 64; t += 2) {
;       float s = 0.f;
;       for (int i = 0; i < w; ++i) s += xps[(15 + t - i) * 128 + c];
;       int cnt = min(w, t0 + t + 1 + nh);
;       float v = s / (float)cnt - xps[(15 + t) * 128 + c];
;       pa[t * 136 + c] = f2bf(v);
;     }
;   }
	v_add_f32_e32 v9, v9, v88
	v_mul_f32_e32 v9, 0.5, v9
	v_sub_f32_e32 v9, v9, v89
	v_cvt_pk_bf16_f32 v9, v9, v9
	ds_write_b16 v7, v9 offset:46432
	v_add_f32_e32 v9, 0, v91
	v_add_f32_e32 v9, v9, v90
	v_mul_f32_e32 v9, 0.5, v9
	v_sub_f32_e32 v9, v9, v91
	v_cvt_pk_bf16_f32 v9, v9, v9
	ds_write_b16 v7, v9 offset:46976
	v_add_f32_e32 v9, 0, v93
	v_add_f32_e32 v9, v9, v92
	v_mul_f32_e32 v9, 0.5, v9
	v_sub_f32_e32 v9, v9, v93
	v_cvt_pk_bf16_f32 v9, v9, v9
	ds_write_b16 v7, v9 offset:47520
	v_add_f32_e32 v9, 0, v95
	v_add_f32_e32 v9, v9, v94
	v_mul_f32_e32 v9, 0.5, v9
	v_sub_f32_e32 v9, v9, v95
	v_cvt_pk_bf16_f32 v9, v9, v9
	ds_write_b16 v7, v9 offset:48064
	v_add_f32_e32 v9, 0, v97
	v_add_f32_e32 v9, v9, v96
	v_mul_f32_e32 v9, 0.5, v9
	v_sub_f32_e32 v9, v9, v97
	v_cvt_pk_bf16_f32 v9, v9, v9
	ds_write_b16 v7, v9 offset:48608
	v_add_f32_e32 v9, 0, v99
	v_add_f32_e32 v9, v9, v98
	v_mul_f32_e32 v9, 0.5, v9
	v_sub_f32_e32 v9, v9, v99
	v_cvt_pk_bf16_f32 v9, v9, v9
	ds_write_b16 v7, v9 offset:49152
	v_add_f32_e32 v9, 0, v101
	v_add_f32_e32 v9, v9, v100
	v_mul_f32_e32 v9, 0.5, v9
	v_sub_f32_e32 v9, v9, v101
	v_cvt_pk_bf16_f32 v9, v9, v9
	ds_write_b16 v7, v9 offset:49696
	v_add_f32_e32 v9, 0, v103
	v_add_f32_e32 v9, v9, v102
	v_mul_f32_e32 v9, 0.5, v9
	v_sub_f32_e32 v9, v9, v103
	v_cvt_pk_bf16_f32 v9, v9, v9
	ds_write_b16 v7, v9 offset:50240
	v_add_f32_e32 v9, 0, v105
	v_add_f32_e32 v9, v9, v104
	v_mul_f32_e32 v9, 0.5, v9
	v_sub_f32_e32 v9, v9, v105
	v_cvt_pk_bf16_f32 v9, v9, v9
	ds_write_b16 v7, v9 offset:50784
	v_add_f32_e32 v9, 0, v107
	v_add_f32_e32 v9, v9, v106
	v_mul_f32_e32 v9, 0.5, v9
	v_sub_f32_e32 v9, v9, v107
	v_cvt_pk_bf16_f32 v9, v9, v9
	ds_write_b16 v7, v9 offset:51328
	v_add_f32_e32 v9, 0, v109
	v_add_f32_e32 v9, v9, v108
	v_mul_f32_e32 v9, 0.5, v9
	v_sub_f32_e32 v9, v9, v109
	v_cvt_pk_bf16_f32 v9, v9, v9
	ds_write_b16 v7, v9 offset:51872
	v_add_f32_e32 v9, 0, v111
	v_add_f32_e32 v9, v9, v110
	v_mul_f32_e32 v9, 0.5, v9
	v_sub_f32_e32 v9, v9, v111
	v_cvt_pk_bf16_f32 v9, v9, v9
	ds_write_b16 v7, v9 offset:52416
	v_add_f32_e32 v9, 0, v113
	v_add_f32_e32 v9, v9, v112
	v_mul_f32_e32 v9, 0.5, v9
	v_sub_f32_e32 v9, v9, v113
	v_cvt_pk_bf16_f32 v9, v9, v9
	ds_write_b16 v7, v9 offset:52960
	v_add_f32_e32 v9, 0, v115
	v_add_f32_e32 v9, v9, v114
	v_mul_f32_e32 v9, 0.5, v9
	v_sub_f32_e32 v9, v9, v115
	v_cvt_pk_bf16_f32 v9, v9, v9
	ds_write_b16 v7, v9 offset:53504
	v_add_f32_e32 v9, 0, v117
	v_add_f32_e32 v9, v9, v116
	v_mul_f32_e32 v9, 0.5, v9
	v_sub_f32_e32 v9, v9, v117
	v_cvt_pk_bf16_f32 v9, v9, v9
	ds_write_b16 v7, v9 offset:54048
	v_add_f32_e32 v9, 0, v119
	v_add_f32_e32 v9, v9, v118
	v_mul_f32_e32 v9, 0.5, v9
	v_sub_f32_e32 v9, v9, v119
	v_cvt_pk_bf16_f32 v9, v9, v9
	ds_write_b16 v7, v9 offset:54592
	v_add_f32_e32 v9, 0, v121
	v_add_f32_e32 v9, v9, v120
	v_mul_f32_e32 v9, 0.5, v9
	v_sub_f32_e32 v9, v9, v121
	v_cvt_pk_bf16_f32 v9, v9, v9
	ds_write_b16 v7, v9 offset:55136
	v_add_f32_e32 v9, 0, v123
	v_add_f32_e32 v9, v9, v122
	v_mul_f32_e32 v9, 0.5, v9
	v_sub_f32_e32 v9, v9, v123
	v_cvt_pk_bf16_f32 v9, v9, v9
	ds_write_b16 v7, v9 offset:55680
	v_add_f32_e32 v9, 0, v125
	v_add_f32_e32 v9, v9, v124
	v_mul_f32_e32 v9, 0.5, v9
	v_sub_f32_e32 v9, v9, v125
	v_cvt_pk_bf16_f32 v9, v9, v9
	ds_write_b16 v7, v9 offset:56224
	v_add_f32_e32 v9, 0, v127
	v_add_f32_e32 v9, v9, v126
	v_mul_f32_e32 v9, 0.5, v9
	v_sub_f32_e32 v9, v9, v127
	v_cvt_pk_bf16_f32 v9, v9, v9
	ds_write_b16 v7, v9 offset:56768
	v_add_f32_e32 v9, 0, v133
	v_add_f32_e32 v9, v9, v132
	v_mul_f32_e32 v9, 0.5, v9
	v_sub_f32_e32 v9, v9, v133
	v_cvt_pk_bf16_f32 v9, v9, v9
	ds_write_b16 v7, v9 offset:57312
	s_mov_b64 s[0:1], -1
	s_branch .LBB0_2518
.Lpl2_w4:
	v_add_f32_e32 v9, 0, v67
	v_add_f32_e32 v9, v9, v66
	v_add_f32_e32 v9, v9, v65
	v_add_f32_e32 v9, v9, v64
	v_mul_f32_e32 v9, 0x3e800000, v9
	v_sub_f32_e32 v9, v9, v67
	v_cvt_pk_bf16_f32 v9, v9, v9
	ds_write_b16 v7, v9 offset:40448
	v_add_f32_e32 v9, 0, v69
	v_add_f32_e32 v9, v9, v68
	v_add_f32_e32 v9, v9, v67
	v_add_f32_e32 v9, v9, v66
	v_mul_f32_e32 v9, 0x3e800000, v9
	v_sub_f32_e32 v9, v9, v69
	v_cvt_pk_bf16_f32 v9, v9, v9
	ds_write_b16 v7, v9 offset:40992
	v_add_f32_e32 v9, 0, v71
	v_add_f32_e32 v9, v9, v70
	v_add_f32_e32 v9, v9, v69
	v_add_f32_e32 v9, v9, v68
	v_mul_f32_e32 v9, 0x3e800000, v9
	v_sub_f32_e32 v9, v9, v71
	v_cvt_pk_bf16_f32 v9, v9, v9
	ds_write_b16 v7, v9 offset:41536
	v_add_f32_e32 v9, 0, v73
	v_add_f32_e32 v9, v9, v72
	v_add_f32_e32 v9, v9, v71
	v_add_f32_e32 v9, v9, v70
	v_mul_f32_e32 v9, 0x3e800000, v9
	v_sub_f32_e32 v9, v9, v73
	v_cvt_pk_bf16_f32 v9, v9, v9
	ds_write_b16 v7, v9 offset:42080
	v_add_f32_e32 v9, 0, v75
	v_add_f32_e32 v9, v9, v74
	v_add_f32_e32 v9, v9, v73
	v_add_f32_e32 v9, v9, v72
	v_mul_f32_e32 v9, 0x3e800000, v9
	v_sub_f32_e32 v9, v9, v75
	v_cvt_pk_bf16_f32 v9, v9, v9
	ds_write_b16 v7, v9 offset:42624
	v_add_f32_e32 v9, 0, v77
	v_add_f32_e32 v9, v9, v76
	v_add_f32_e32 v9, v9, v75
	v_add_f32_e32 v9, v9, v74
	v_mul_f32_e32 v9, 0x3e800000, v9
	v_sub_f32_e32 v9, v9, v77
	v_cvt_pk_bf16_f32 v9, v9, v9
	ds_write_b16 v7, v9 offset:43168
	v_add_f32_e32 v9, 0, v79
	v_add_f32_e32 v9, v9, v78
	v_add_f32_e32 v9, v9, v77
	v_add_f32_e32 v9, v9, v76
	v_mul_f32_e32 v9, 0x3e800000, v9
	v_sub_f32_e32 v9, v9, v79
	v_cvt_pk_bf16_f32 v9, v9, v9
	ds_write_b16 v7, v9 offset:43712
	v_add_f32_e32 v9, 0, v81
	v_add_f32_e32 v9, v9, v80
	v_add_f32_e32 v9, v9, v79
	v_add_f32_e32 v9, v9, v78
	v_mul_f32_e32 v9, 0x3e800000, v9
	v_sub_f32_e32 v9, v9, v81
	v_cvt_pk_bf16_f32 v9, v9, v9
	ds_write_b16 v7, v9 offset:44256
	v_add_f32_e32 v9, 0, v83
	v_add_f32_e32 v9, v9, v82
	v_add_f32_e32 v9, v9, v81
	v_add_f32_e32 v9, v9, v80
; DI bfr f2bf(float x) { return (bfr)(pack2(x, 0.f) & 0xFFFFu); }
; DI void pool_item(const Params& p, int layer, int isP, int sq, int tile, int g, char*) {
;     ...
;   {
;     const int c = tid & 127;
;     const int w = 2 << g;
;     const int nh = isP ? 0 : PAST;
;     for (int t = tid >> 7; t < 64; t += 2) {
;       float s = 0.f;
;       for (int i = 0; i < w; ++i) s += xps[(15 + t - i) * 128 + c];
;       int cnt = min(w, t0 + t + 1 + nh);
;       float v = s / (float)cnt - xps[(15 + t) * 128 + c];
;       pa[t * 136 + c] = f2bf(v);
;     }
;   }
	v_mul_f32_e32 v9, 0x3e800000, v9
	v_sub_f32_e32 v9, v9, v83
	v_cvt_pk_bf16_f32 v9, v9, v9
	ds_write_b16 v7, v9 offset:44800
	v_add_f32_e32 v9, 0, v85
	v_add_f32_e32 v9, v9, v84
	v_add_f32_e32 v9, v9, v83
	v_add_f32_e32 v9, v9, v82
	v_mul_f32_e32 v9, 0x3e800000, v9
	v_sub_f32_e32 v9, v9, v85
	v_cvt_pk_bf16_f32 v9, v9, v9
	ds_write_b16 v7, v9 offset:45344
	v_add_f32_e32 v9, 0, v87
	v_add_f32_e32 v9, v9, v86
	v_add_f32_e32 v9, v9, v85
	v_add_f32_e32 v9, v9, v84
	v_mul_f32_e32 v9, 0x3e800000, v9
	v_sub_f32_e32 v9, v9, v87
	v_cvt_pk_bf16_f32 v9, v9, v9
	ds_write_b16 v7, v9 offset:45888
	v_add_f32_e32 v9, 0, v89
	v_add_f32_e32 v9, v9, v88
	v_add_f32_e32 v9, v9, v87
	v_add_f32_e32 v9, v9, v86
	v_mul_f32_e32 v9, 0x3e800000, v9
	v_sub_f32_e32 v9, v9, v89
	v_cvt_pk_bf16_f32 v9, v9, v9
	ds_write_b16 v7, v9 offset:46432
	v_add_f32_e32 v9, 0, v91
	v_add_f32_e32 v9, v9, v90
	v_add_f32_e32 v9, v9, v89
	v_add_f32_e32 v9, v9, v88
	v_mul_f32_e32 v9, 0x3e800000, v9
	v_sub_f32_e32 v9, v9, v91
	v_cvt_pk_bf16_f32 v9, v9, v9
	ds_write_b16 v7, v9 offset:46976
	v_add_f32_e32 v9, 0, v93
	v_add_f32_e32 v9, v9, v92
	v_add_f32_e32 v9, v9, v91
	v_add_f32_e32 v9, v9, v90
	v_mul_f32_e32 v9, 0x3e800000, v9
	v_sub_f32_e32 v9, v9, v93
	v_cvt_pk_bf16_f32 v9, v9, v9
	ds_write_b16 v7, v9 offset:47520
	v_add_f32_e32 v9, 0, v95
	v_add_f32_e32 v9, v9, v94
	v_add_f32_e32 v9, v9, v93
	v_add_f32_e32 v9, v9, v92
	v_mul_f32_e32 v9, 0x3e800000, v9
	v_sub_f32_e32 v9, v9, v95
	v_cvt_pk_bf16_f32 v9, v9, v9
	ds_write_b16 v7, v9 offset:48064
	v_add_f32_e32 v9, 0, v97
	v_add_f32_e32 v9, v9, v96
	v_add_f32_e32 v9, v9, v95
	v_add_f32_e32 v9, v9, v94
	v_mul_f32_e32 v9, 0x3e800000, v9
	v_sub_f32_e32 v9, v9, v97
	v_cvt_pk_bf16_f32 v9, v9, v9
	ds_write_b16 v7, v9 offset:48608
	v_add_f32_e32 v9, 0, v99
	v_add_f32_e32 v9, v9, v98
	v_add_f32_e32 v9, v9, v97
	v_add_f32_e32 v9, v9, v96
	v_mul_f32_e32 v9, 0x3e800000, v9
	v_sub_f32_e32 v9, v9, v99
	v_cvt_pk_bf16_f32 v9, v9, v9
	ds_write_b16 v7, v9 offset:49152
	v_add_f32_e32 v9, 0, v101
	v_add_f32_e32 v9, v9, v100
	v_add_f32_e32 v9, v9, v99
	v_add_f32_e32 v9, v9, v98
	v_mul_f32_e32 v9, 0x3e800000, v9
	v_sub_f32_e32 v9, v9, v101
	v_cvt_pk_bf16_f32 v9, v9, v9
	ds_write_b16 v7, v9 offset:49696
	v_add_f32_e32 v9, 0, v103
	v_add_f32_e32 v9, v9, v102
	v_add_f32_e32 v9, v9, v101
	v_add_f32_e32 v9, v9, v100
	v_mul_f32_e32 v9, 0x3e800000, v9
	v_sub_f32_e32 v9, v9, v103
	v_cvt_pk_bf16_f32 v9, v9, v9
	ds_write_b16 v7, v9 offset:50240
	v_add_f32_e32 v9, 0, v105
	v_add_f32_e32 v9, v9, v104
	v_add_f32_e32 v9, v9, v103
	v_add_f32_e32 v9, v9, v102
	v_mul_f32_e32 v9, 0x3e800000, v9
	v_sub_f32_e32 v9, v9, v105
	v_cvt_pk_bf16_f32 v9, v9, v9
	ds_write_b16 v7, v9 offset:50784
	v_add_f32_e32 v9, 0, v107
	v_add_f32_e32 v9, v9, v106
	v_add_f32_e32 v9, v9, v105
	v_add_f32_e32 v9, v9, v104
	v_mul_f32_e32 v9, 0x3e800000, v9
	v_sub_f32_e32 v9, v9, v107
	v_cvt_pk_bf16_f32 v9, v9, v9
	ds_write_b16 v7, v9 offset:51328
	v_add_f32_e32 v9, 0, v109
	v_add_f32_e32 v9, v9, v108
	v_add_f32_e32 v9, v9, v107
	v_add_f32_e32 v9, v9, v106
	v_mul_f32_e32 v9, 0x3e800000, v9
	v_sub_f32_e32 v9, v9, v109
	v_cvt_pk_bf16_f32 v9, v9, v9
	ds_write_b16 v7, v9 offset:51872
	v_add_f32_e32 v9, 0, v111
	v_add_f32_e32 v9, v9, v110
	v_add_f32_e32 v9, v9, v109
	v_add_f32_e32 v9, v9, v108
	v_mul_f32_e32 v9, 0x3e800000, v9
	v_sub_f32_e32 v9, v9, v111
	v_cvt_pk_bf16_f32 v9, v9, v9
	ds_write_b16 v7, v9 offset:52416
	v_add_f32_e32 v9, 0, v113
	v_add_f32_e32 v9, v9, v112
	v_add_f32_e32 v9, v9, v111
	v_add_f32_e32 v9, v9, v110
	v_mul_f32_e32 v9, 0x3e800000, v9
	v_sub_f32_e32 v9, v9, v113
	v_cvt_pk_bf16_f32 v9, v9, v9
	ds_write_b16 v7, v9 offset:52960
	v_add_f32_e32 v9, 0, v115
	v_add_f32_e32 v9, v9, v114
	v_add_f32_e32 v9, v9, v113
	v_add_f32_e32 v9, v9, v112
	v_mul_f32_e32 v9, 0x3e800000, v9
	v_sub_f32_e32 v9, v9, v115
	v_cvt_pk_bf16_f32 v9, v9, v9
	ds_write_b16 v7, v9 offset:53504
	v_add_f32_e32 v9, 0, v117
	v_add_f32_e32 v9, v9, v116
	v_add_f32_e32 v9, v9, v115
	v_add_f32_e32 v9, v9, v114
	v_mul_f32_e32 v9, 0x3e800000, v9
	v_sub_f32_e32 v9, v9, v117
	v_cvt_pk_bf16_f32 v9, v9, v9
	ds_write_b16 v7, v9 offset:54048
	v_add_f32_e32 v9, 0, v119
	v_add_f32_e32 v9, v9, v118
	v_add_f32_e32 v9, v9, v117
	v_add_f32_e32 v9, v9, v116
	v_mul_f32_e32 v9, 0x3e800000, v9
	v_sub_f32_e32 v9, v9, v119
	v_cvt_pk_bf16_f32 v9, v9, v9
	ds_write_b16 v7, v9 offset:54592
	v_add_f32_e32 v9, 0, v121
	v_add_f32_e32 v9, v9, v120
	v_add_f32_e32 v9, v9, v119
	v_add_f32_e32 v9, v9, v118
	v_mul_f32_e32 v9, 0x3e800000, v9
	v_sub_f32_e32 v9, v9, v121
	v_cvt_pk_bf16_f32 v9, v9, v9
	ds_write_b16 v7, v9 offset:55136
	v_add_f32_e32 v9, 0, v123
	v_add_f32_e32 v9, v9, v122
	v_add_f32_e32 v9, v9, v121
	v_add_f32_e32 v9, v9, v120
	v_mul_f32_e32 v9, 0x3e800000, v9
	v_sub_f32_e32 v9, v9, v123
	v_cvt_pk_bf16_f32 v9, v9, v9
	ds_write_b16 v7, v9 offset:55680
	v_add_f32_e32 v9, 0, v125
	v_add_f32_e32 v9, v9, v124
	v_add_f32_e32 v9, v9, v123
	v_add_f32_e32 v9, v9, v122
	v_mul_f32_e32 v9, 0x3e800000, v9
	v_sub_f32_e32 v9, v9, v125
	v_cvt_pk_bf16_f32 v9, v9, v9
	ds_write_b16 v7, v9 offset:56224
	v_add_f32_e32 v9, 0, v127
	v_add_f32_e32 v9, v9, v126
	v_add_f32_e32 v9, v9, v125
	v_add_f32_e32 v9, v9, v124
	v_mul_f32_e32 v9, 0x3e800000, v9
	v_sub_f32_e32 v9, v9, v127
	v_cvt_pk_bf16_f32 v9, v9, v9
	ds_write_b16 v7, v9 offset:56768
	v_add_f32_e32 v9, 0, v133
	v_add_f32_e32 v9, v9, v132
	v_add_f32_e32 v9, v9, v127
	v_add_f32_e32 v9, v9, v126
	v_mul_f32_e32 v9, 0x3e800000, v9
	v_sub_f32_e32 v9, v9, v133
	v_cvt_pk_bf16_f32 v9, v9, v9
	ds_write_b16 v7, v9 offset:57312
	s_mov_b64 s[0:1], -1
	s_branch .LBB0_2518
; DI bfr f2bf(float x) { return (bfr)(pack2(x, 0.f) & 0xFFFFu); }
; DI void pool_item(const Params& p, int layer, int isP, int sq, int tile, int g, char*) {
;     ...
;   {
;     const int c = tid & 127;
;     const int w = 2 << g;
;     const int nh = isP ? 0 : PAST;
;     for (int t = tid >> 7; t < 64; t += 2) {
;       float s = 0.f;
;       for (int i = 0; i < w; ++i) s += xps[(15 + t - i) * 128 + c];
;       int cnt = min(w, t0 + t + 1 + nh);
;       float v = s / (float)cnt - xps[(15 + t) * 128 + c];
;       pa[t * 136 + c] = f2bf(v);
;     }
;   }
.Lpl2_w8:
	v_add_f32_e32 v9, 0, v67
	v_add_f32_e32 v9, v9, v66
	v_add_f32_e32 v9, v9, v65
	v_add_f32_e32 v9, v9, v64
	v_add_f32_e32 v9, v9, v63
	v_add_f32_e32 v9, v9, v62
	v_add_f32_e32 v9, v9, v61
	v_add_f32_e32 v9, v9, v60
	v_mul_f32_e32 v9, 0x3e000000, v9
	v_sub_f32_e32 v9, v9, v67
	v_cvt_pk_bf16_f32 v9, v9, v9
	ds_write_b16 v7, v9 offset:40448
	v_add_f32_e32 v9, 0, v69
	v_add_f32_e32 v9, v9, v68
	v_add_f32_e32 v9, v9, v67
	v_add_f32_e32 v9, v9, v66
	v_add_f32_e32 v9, v9, v65
	v_add_f32_e32 v9, v9, v64
	v_add_f32_e32 v9, v9, v63
	v_add_f32_e32 v9, v9, v62
	v_mul_f32_e32 v9, 0x3e000000, v9
	v_sub_f32_e32 v9, v9, v69
	v_cvt_pk_bf16_f32 v9, v9, v9
	ds_write_b16 v7, v9 offset:40992
	v_add_f32_e32 v9, 0, v71
	v_add_f32_e32 v9, v9, v70
	v_add_f32_e32 v9, v9, v69
	v_add_f32_e32 v9, v9, v68
	v_add_f32_e32 v9, v9, v67
	v_add_f32_e32 v9, v9, v66
	v_add_f32_e32 v9, v9, v65
	v_add_f32_e32 v9, v9, v64
	v_mul_f32_e32 v9, 0x3e000000, v9
	v_sub_f32_e32 v9, v9, v71
	v_cvt_pk_bf16_f32 v9, v9, v9
	ds_write_b16 v7, v9 offset:41536
	v_add_f32_e32 v9, 0, v73
	v_add_f32_e32 v9, v9, v72
	v_add_f32_e32 v9, v9, v71
	v_add_f32_e32 v9, v9, v70
	v_add_f32_e32 v9, v9, v69
	v_add_f32_e32 v9, v9, v68
	v_add_f32_e32 v9, v9, v67
	v_add_f32_e32 v9, v9, v66
	v_mul_f32_e32 v9, 0x3e000000, v9
	v_sub_f32_e32 v9, v9, v73
	v_cvt_pk_bf16_f32 v9, v9, v9
	ds_write_b16 v7, v9 offset:42080
	v_add_f32_e32 v9, 0, v75
	v_add_f32_e32 v9, v9, v74
	v_add_f32_e32 v9, v9, v73
	v_add_f32_e32 v9, v9, v72
	v_add_f32_e32 v9, v9, v71
	v_add_f32_e32 v9, v9, v70
	v_add_f32_e32 v9, v9, v69
	v_add_f32_e32 v9, v9, v68
	v_mul_f32_e32 v9, 0x3e000000, v9
	v_sub_f32_e32 v9, v9, v75
	v_cvt_pk_bf16_f32 v9, v9, v9
	ds_write_b16 v7, v9 offset:42624
	v_add_f32_e32 v9, 0, v77
	v_add_f32_e32 v9, v9, v76
	v_add_f32_e32 v9, v9, v75
	v_add_f32_e32 v9, v9, v74
	v_add_f32_e32 v9, v9, v73
	v_add_f32_e32 v9, v9, v72
	v_add_f32_e32 v9, v9, v71
	v_add_f32_e32 v9, v9, v70
	v_mul_f32_e32 v9, 0x3e000000, v9
	v_sub_f32_e32 v9, v9, v77
	v_cvt_pk_bf16_f32 v9, v9, v9
	ds_write_b16 v7, v9 offset:43168
	v_add_f32_e32 v9, 0, v79
	v_add_f32_e32 v9, v9, v78
	v_add_f32_e32 v9, v9, v77
	v_add_f32_e32 v9, v9, v76
	v_add_f32_e32 v9, v9, v75
	v_add_f32_e32 v9, v9, v74
	v_add_f32_e32 v9, v9, v73
	v_add_f32_e32 v9, v9, v72
	v_mul_f32_e32 v9, 0x3e000000, v9
	v_sub_f32_e32 v9, v9, v79
	v_cvt_pk_bf16_f32 v9, v9, v9
	ds_write_b16 v7, v9 offset:43712
	v_add_f32_e32 v9, 0, v81
	v_add_f32_e32 v9, v9, v80
	v_add_f32_e32 v9, v9, v79
	v_add_f32_e32 v9, v9, v78
	v_add_f32_e32 v9, v9, v77
	v_add_f32_e32 v9, v9, v76
	v_add_f32_e32 v9, v9, v75
	v_add_f32_e32 v9, v9, v74
	v_mul_f32_e32 v9, 0x3e000000, v9
	v_sub_f32_e32 v9, v9, v81
	v_cvt_pk_bf16_f32 v9, v9, v9
	ds_write_b16 v7, v9 offset:44256
	v_add_f32_e32 v9, 0, v83
	v_add_f32_e32 v9, v9, v82
	v_add_f32_e32 v9, v9, v81
	v_add_f32_e32 v9, v9, v80
	v_add_f32_e32 v9, v9, v79
	v_add_f32_e32 v9, v9, v78
	v_add_f32_e32 v9, v9, v77
	v_add_f32_e32 v9, v9, v76
	v_mul_f32_e32 v9, 0x3e000000, v9
	v_sub_f32_e32 v9, v9, v83
	v_cvt_pk_bf16_f32 v9, v9, v9
	ds_write_b16 v7, v9 offset:44800
	v_add_f32_e32 v9, 0, v85
	v_add_f32_e32 v9, v9, v84
	v_add_f32_e32 v9, v9, v83
	v_add_f32_e32 v9, v9, v82
	v_add_f32_e32 v9, v9, v81
	v_add_f32_e32 v9, v9, v80
	v_add_f32_e32 v9, v9, v79
	v_add_f32_e32 v9, v9, v78
	v_mul_f32_e32 v9, 0x3e000000, v9
	v_sub_f32_e32 v9, v9, v85
	v_cvt_pk_bf16_f32 v9, v9, v9
	ds_write_b16 v7, v9 offset:45344
	v_add_f32_e32 v9, 0, v87
	v_add_f32_e32 v9, v9, v86
	v_add_f32_e32 v9, v9, v85
	v_add_f32_e32 v9, v9, v84
	v_add_f32_e32 v9, v9, v83
	v_add_f32_e32 v9, v9, v82
	v_add_f32_e32 v9, v9, v81
	v_add_f32_e32 v9, v9, v80
	v_mul_f32_e32 v9, 0x3e000000, v9
	v_sub_f32_e32 v9, v9, v87
	v_cvt_pk_bf16_f32 v9, v9, v9
	ds_write_b16 v7, v9 offset:45888
	v_add_f32_e32 v9, 0, v89
	v_add_f32_e32 v9, v9, v88
	v_add_f32_e32 v9, v9, v87
	v_add_f32_e32 v9, v9, v86
	v_add_f32_e32 v9, v9, v85
	v_add_f32_e32 v9, v9, v84
	v_add_f32_e32 v9, v9, v83
	v_add_f32_e32 v9, v9, v82
	v_mul_f32_e32 v9, 0x3e000000, v9
	v_sub_f32_e32 v9, v9, v89
	v_cvt_pk_bf16_f32 v9, v9, v9
	ds_write_b16 v7, v9 offset:46432
	v_add_f32_e32 v9, 0, v91
	v_add_f32_e32 v9, v9, v90
	v_add_f32_e32 v9, v9, v89
	v_add_f32_e32 v9, v9, v88
	v_add_f32_e32 v9, v9, v87
	v_add_f32_e32 v9, v9, v86
	v_add_f32_e32 v9, v9, v85
	v_add_f32_e32 v9, v9, v84
	v_mul_f32_e32 v9, 0x3e000000, v9
	v_sub_f32_e32 v9, v9, v91
	v_cvt_pk_bf16_f32 v9, v9, v9
	ds_write_b16 v7, v9 offset:46976
	v_add_f32_e32 v9, 0, v93
	v_add_f32_e32 v9, v9, v92
	v_add_f32_e32 v9, v9, v91
	v_add_f32_e32 v9, v9, v90
	v_add_f32_e32 v9, v9, v89
	v_add_f32_e32 v9, v9, v88
	v_add_f32_e32 v9, v9, v87
	v_add_f32_e32 v9, v9, v86
	v_mul_f32_e32 v9, 0x3e000000, v9
	v_sub_f32_e32 v9, v9, v93
	v_cvt_pk_bf16_f32 v9, v9, v9
	ds_write_b16 v7, v9 offset:47520
	v_add_f32_e32 v9, 0, v95
	v_add_f32_e32 v9, v9, v94
	v_add_f32_e32 v9, v9, v93
	v_add_f32_e32 v9, v9, v92
	v_add_f32_e32 v9, v9, v91
	v_add_f32_e32 v9, v9, v90
	v_add_f32_e32 v9, v9, v89
	v_add_f32_e32 v9, v9, v88
	v_mul_f32_e32 v9, 0x3e000000, v9
	v_sub_f32_e32 v9, v9, v95
	v_cvt_pk_bf16_f32 v9, v9, v9
	ds_write_b16 v7, v9 offset:48064
	v_add_f32_e32 v9, 0, v97
	v_add_f32_e32 v9, v9, v96
	v_add_f32_e32 v9, v9, v95
	v_add_f32_e32 v9, v9, v94
	v_add_f32_e32 v9, v9, v93
	v_add_f32_e32 v9, v9, v92
	v_add_f32_e32 v9, v9, v91
	v_add_f32_e32 v9, v9, v90
	v_mul_f32_e32 v9, 0x3e000000, v9
	v_sub_f32_e32 v9, v9, v97
	v_cvt_pk_bf16_f32 v9, v9, v9
	ds_write_b16 v7, v9 offset:48608
	v_add_f32_e32 v9, 0, v99
	v_add_f32_e32 v9, v9, v98
	v_add_f32_e32 v9, v9, v97
	v_add_f32_e32 v9, v9, v96
	v_add_f32_e32 v9, v9, v95
	v_add_f32_e32 v9, v9, v94
	v_add_f32_e32 v9, v9, v93
; DI bfr f2bf(float x) { return (bfr)(pack2(x, 0.f) & 0xFFFFu); }
; DI void pool_item(const Params& p, int layer, int isP, int sq, int tile, int g, char*) {
;     ...
;   {
;     const int c = tid & 127;
;     const int w = 2 << g;
;     const int nh = isP ? 0 : PAST;
;     for (int t = tid >> 7; t < 64; t += 2) {
;       float s = 0.f;
;       for (int i = 0; i < w; ++i) s += xps[(15 + t - i) * 128 + c];
;       int cnt = min(w, t0 + t + 1 + nh);
;       float v = s / (float)cnt - xps[(15 + t) * 128 + c];
;       pa[t * 136 + c] = f2bf(v);
;     }
;   }
	v_add_f32_e32 v9, v9, v92
	v_mul_f32_e32 v9, 0x3e000000, v9
	v_sub_f32_e32 v9, v9, v99
	v_cvt_pk_bf16_f32 v9, v9, v9
	ds_write_b16 v7, v9 offset:49152
	v_add_f32_e32 v9, 0, v101
	v_add_f32_e32 v9, v9, v100
	v_add_f32_e32 v9, v9, v99
	v_add_f32_e32 v9, v9, v98
	v_add_f32_e32 v9, v9, v97
	v_add_f32_e32 v9, v9, v96
	v_add_f32_e32 v9, v9, v95
	v_add_f32_e32 v9, v9, v94
	v_mul_f32_e32 v9, 0x3e000000, v9
	v_sub_f32_e32 v9, v9, v101
	v_cvt_pk_bf16_f32 v9, v9, v9
	ds_write_b16 v7, v9 offset:49696
	v_add_f32_e32 v9, 0, v103
	v_add_f32_e32 v9, v9, v102
	v_add_f32_e32 v9, v9, v101
	v_add_f32_e32 v9, v9, v100
	v_add_f32_e32 v9, v9, v99
	v_add_f32_e32 v9, v9, v98
	v_add_f32_e32 v9, v9, v97
	v_add_f32_e32 v9, v9, v96
	v_mul_f32_e32 v9, 0x3e000000, v9
	v_sub_f32_e32 v9, v9, v103
	v_cvt_pk_bf16_f32 v9, v9, v9
	ds_write_b16 v7, v9 offset:50240
	v_add_f32_e32 v9, 0, v105
	v_add_f32_e32 v9, v9, v104
	v_add_f32_e32 v9, v9, v103
	v_add_f32_e32 v9, v9, v102
	v_add_f32_e32 v9, v9, v101
	v_add_f32_e32 v9, v9, v100
	v_add_f32_e32 v9, v9, v99
	v_add_f32_e32 v9, v9, v98
	v_mul_f32_e32 v9, 0x3e000000, v9
	v_sub_f32_e32 v9, v9, v105
	v_cvt_pk_bf16_f32 v9, v9, v9
	ds_write_b16 v7, v9 offset:50784
	v_add_f32_e32 v9, 0, v107
	v_add_f32_e32 v9, v9, v106
	v_add_f32_e32 v9, v9, v105
	v_add_f32_e32 v9, v9, v104
	v_add_f32_e32 v9, v9, v103
	v_add_f32_e32 v9, v9, v102
	v_add_f32_e32 v9, v9, v101
	v_add_f32_e32 v9, v9, v100
	v_mul_f32_e32 v9, 0x3e000000, v9
	v_sub_f32_e32 v9, v9, v107
	v_cvt_pk_bf16_f32 v9, v9, v9
	ds_write_b16 v7, v9 offset:51328
	v_add_f32_e32 v9, 0, v109
	v_add_f32_e32 v9, v9, v108
	v_add_f32_e32 v9, v9, v107
	v_add_f32_e32 v9, v9, v106
	v_add_f32_e32 v9, v9, v105
	v_add_f32_e32 v9, v9, v104
	v_add_f32_e32 v9, v9, v103
	v_add_f32_e32 v9, v9, v102
	v_mul_f32_e32 v9, 0x3e000000, v9
	v_sub_f32_e32 v9, v9, v109
	v_cvt_pk_bf16_f32 v9, v9, v9
	ds_write_b16 v7, v9 offset:51872
	v_add_f32_e32 v9, 0, v111
	v_add_f32_e32 v9, v9, v110
	v_add_f32_e32 v9, v9, v109
	v_add_f32_e32 v9, v9, v108
	v_add_f32_e32 v9, v9, v107
	v_add_f32_e32 v9, v9, v106
	v_add_f32_e32 v9, v9, v105
	v_add_f32_e32 v9, v9, v104
	v_mul_f32_e32 v9, 0x3e000000, v9
	v_sub_f32_e32 v9, v9, v111
	v_cvt_pk_bf16_f32 v9, v9, v9
	ds_write_b16 v7, v9 offset:52416
	v_add_f32_e32 v9, 0, v113
	v_add_f32_e32 v9, v9, v112
	v_add_f32_e32 v9, v9, v111
	v_add_f32_e32 v9, v9, v110
	v_add_f32_e32 v9, v9, v109
	v_add_f32_e32 v9, v9, v108
	v_add_f32_e32 v9, v9, v107
	v_add_f32_e32 v9, v9, v106
	v_mul_f32_e32 v9, 0x3e000000, v9
	v_sub_f32_e32 v9, v9, v113
	v_cvt_pk_bf16_f32 v9, v9, v9
	ds_write_b16 v7, v9 offset:52960
	v_add_f32_e32 v9, 0, v115
	v_add_f32_e32 v9, v9, v114
	v_add_f32_e32 v9, v9, v113
	v_add_f32_e32 v9, v9, v112
	v_add_f32_e32 v9, v9, v111
	v_add_f32_e32 v9, v9, v110
	v_add_f32_e32 v9, v9, v109
	v_add_f32_e32 v9, v9, v108
	v_mul_f32_e32 v9, 0x3e000000, v9
	v_sub_f32_e32 v9, v9, v115
	v_cvt_pk_bf16_f32 v9, v9, v9
	ds_write_b16 v7, v9 offset:53504
	v_add_f32_e32 v9, 0, v117
	v_add_f32_e32 v9, v9, v116
	v_add_f32_e32 v9, v9, v115
	v_add_f32_e32 v9, v9, v114
	v_add_f32_e32 v9, v9, v113
	v_add_f32_e32 v9, v9, v112
	v_add_f32_e32 v9, v9, v111
	v_add_f32_e32 v9, v9, v110
	v_mul_f32_e32 v9, 0x3e000000, v9
	v_sub_f32_e32 v9, v9, v117
	v_cvt_pk_bf16_f32 v9, v9, v9
	ds_write_b16 v7, v9 offset:54048
	v_add_f32_e32 v9, 0, v119
	v_add_f32_e32 v9, v9, v118
	v_add_f32_e32 v9, v9, v117
	v_add_f32_e32 v9, v9, v116
	v_add_f32_e32 v9, v9, v115
	v_add_f32_e32 v9, v9, v114
	v_add_f32_e32 v9, v9, v113
	v_add_f32_e32 v9, v9, v112
	v_mul_f32_e32 v9, 0x3e000000, v9
	v_sub_f32_e32 v9, v9, v119
	v_cvt_pk_bf16_f32 v9, v9, v9
	ds_write_b16 v7, v9 offset:54592
	v_add_f32_e32 v9, 0, v121
	v_add_f32_e32 v9, v9, v120
	v_add_f32_e32 v9, v9, v119
	v_add_f32_e32 v9, v9, v118
	v_add_f32_e32 v9, v9, v117
	v_add_f32_e32 v9, v9, v116
	v_add_f32_e32 v9, v9, v115
	v_add_f32_e32 v9, v9, v114
	v_mul_f32_e32 v9, 0x3e000000, v9
	v_sub_f32_e32 v9, v9, v121
	v_cvt_pk_bf16_f32 v9, v9, v9
	ds_write_b16 v7, v9 offset:55136
	v_add_f32_e32 v9, 0, v123
	v_add_f32_e32 v9, v9, v122
	v_add_f32_e32 v9, v9, v121
	v_add_f32_e32 v9, v9, v120
	v_add_f32_e32 v9, v9, v119
	v_add_f32_e32 v9, v9, v118
	v_add_f32_e32 v9, v9, v117
	v_add_f32_e32 v9, v9, v116
	v_mul_f32_e32 v9, 0x3e000000, v9
	v_sub_f32_e32 v9, v9, v123
	v_cvt_pk_bf16_f32 v9, v9, v9
	ds_write_b16 v7, v9 offset:55680
	v_add_f32_e32 v9, 0, v125
	v_add_f32_e32 v9, v9, v124
	v_add_f32_e32 v9, v9, v123
	v_add_f32_e32 v9, v9, v122
	v_add_f32_e32 v9, v9, v121
	v_add_f32_e32 v9, v9, v120
	v_add_f32_e32 v9, v9, v119
	v_add_f32_e32 v9, v9, v118
	v_mul_f32_e32 v9, 0x3e000000, v9
	v_sub_f32_e32 v9, v9, v125
	v_cvt_pk_bf16_f32 v9, v9, v9
	ds_write_b16 v7, v9 offset:56224
	v_add_f32_e32 v9, 0, v127
	v_add_f32_e32 v9, v9, v126
	v_add_f32_e32 v9, v9, v125
	v_add_f32_e32 v9, v9, v124
	v_add_f32_e32 v9, v9, v123
	v_add_f32_e32 v9, v9, v122
	v_add_f32_e32 v9, v9, v121
	v_add_f32_e32 v9, v9, v120
	v_mul_f32_e32 v9, 0x3e000000, v9
	v_sub_f32_e32 v9, v9, v127
	v_cvt_pk_bf16_f32 v9, v9, v9
	ds_write_b16 v7, v9 offset:56768
	v_add_f32_e32 v9, 0, v133
	v_add_f32_e32 v9, v9, v132
	v_add_f32_e32 v9, v9, v127
	v_add_f32_e32 v9, v9, v126
	v_add_f32_e32 v9, v9, v125
	v_add_f32_e32 v9, v9, v124
	v_add_f32_e32 v9, v9, v123
	v_add_f32_e32 v9, v9, v122
	v_mul_f32_e32 v9, 0x3e000000, v9
	v_sub_f32_e32 v9, v9, v133
	v_cvt_pk_bf16_f32 v9, v9, v9
	ds_write_b16 v7, v9 offset:57312
	s_mov_b64 s[0:1], -1
	s_branch .LBB0_2518
.Lpl2_slow:
	v_lshlrev_b32_e32 v1, 2, v4
	v_lshl_or_b32 v1, v3, 9, v1
	v_readlane_b32 s2, v251, 33
	s_lshl_b32 s4, 2, s19
	v_lshl_add_u32 v0, v4, 1, v169
	s_or_b32 s5, s17, 1
	v_add_u32_e32 v1, s2, v1
	s_mov_b64 s[2:3], 0

; #define MFMA16(a, b, c) __builtin_amdgcn_mfma_f32_16x16x32_bf16((a), (b), (c), 0, 0, 0)
; DI float bf2f(bfr b) { return __uint_as_float(((unsigned)b) << 16); }
; DI bfr f2bf(float x) { return (bfr)(pack2(x, 0.f) & 0xFFFFu); }
; DI void pool_item(const Params& p, int layer, int isP, int sq, int tile, int g, char*) {
;     ...
;   {
;     const bfr* PwT = (const bfr*)(p.ws + W_PWT) + (long)(layer * 4 + g) * 16384;
;     bf16x8 af[4];
; #pragma unroll
;     for (int ks = 0; ks < 4; ++ks) af[ks] = *(const bf16x8*)(pa + (wid * 16 + fr) * 136 + ks * 32 + fq * 8);
; #pragma unroll
;     for (int nt = 0; nt < 8; ++nt) {
;       const int d = nt * 16 + fr;
;       f32x4 acc = {0.f, 0.f, 0.f, 0.f};
; #pragma unroll
;       for (int ks = 0; ks < 4; ++ks) {
;         bf16x8 bq = *(const bf16x8*)(PwT + d * 128 + ks * 32 + fq * 8);
;         acc = MFMA16(af[ks], bq, acc);
;       }
;       const float scl = p.pool_scale[layer * 512 + ch0 + d];
; #pragma unroll
;       for (int j = 0; j < 4; ++j) {
;         const int t = wid * 16 + fq * 4 + j;
;         if (t0 + t < T) {
;           const long idx = (long)(rowbase + t0 + t) * 512 + ch0 + d;
;           gcy[idx] = f2bf(acc[j] * scl * bf2f(gcy[idx]));
;         }
;       }
.LBB0_2518:
	s_or_b64 exec, exec, s[0:1]
	v_readlane_b32 s2, v251, 45
	v_readlane_b32 s3, v251, 46
	s_or_b32 s2, s19, s2
	s_ashr_i32 s1, s18, 2
	s_ashr_i32 s3, s2, 31
	s_and_b32 s4, s1, -16
	v_bfi_b32 v0, -16, s1, v2
	s_movk_i32 s1, 0x110
	s_lshl_b32 s0, s19, 7
	s_lshl_b64 s[2:3], s[2:3], 15
	v_mul_lo_u32 v0, v0, s1
	v_readlane_b32 s1, v251, 57
	v_bfe_u32 v16, v2, 4, 2
	s_add_u32 s2, s1, s2
	v_readlane_b32 s1, v251, 58
	v_and_b32_e32 v20, 15, v2
	v_lshlrev_b32_e32 v128, 4, v16
	s_addc_u32 s3, s1, s3
	v_add3_u32 v0, s78, v0, v128
	v_lshl_add_u64 v[22:23], s[2:3], 0, v[128:129]
	v_lshlrev_b32_e32 v128, 8, v20
	v_lshl_add_u64 v[28:29], v[22:23], 0, v[128:129]
	s_waitcnt lgkmcnt(0)
	s_barrier
	ds_read_b128 v[12:15], v0 offset:40448
	ds_read_b128 v[8:11], v0 offset:40512
	ds_read_b128 v[4:7], v0 offset:40576
	ds_read_b128 v[0:3], v0 offset:40640
	v_lshl_or_b32 v21, v16, 2, s4
	global_load_dwordx4 v[16:19], v[28:29], off
	global_load_dwordx4 v[24:27], v[28:29], off offset:64
	v_readlane_b32 s1, v251, 50
	s_or_b32 s6, s0, s1
	v_readlane_b32 s36, v249, 38
	v_readlane_b32 s42, v249, 44
	v_readlane_b32 s43, v249, 45
	s_sub_i32 s7, 0x1010, s17
	s_add_i32 s17, s17, s16
	s_lshl_b32 s0, s0, 1
	v_readlane_b32 s1, v251, 55
	s_add_u32 s0, s1, s0
	v_readlane_b32 s1, v251, 56
	s_addc_u32 s1, s1, 0
	v_lshlrev_b32_e32 v128, 1, v20
	v_cmp_gt_i32_e32 vcc, s7, v21
	v_readlane_b32 s37, v249, 39
	v_readlane_b32 s38, v249, 40
	v_readlane_b32 s39, v249, 41
	v_readlane_b32 s40, v249, 42
	v_readlane_b32 s41, v249, 43
	v_readlane_b32 s44, v249, 46
	v_readlane_b32 s45, v249, 47
	v_readlane_b32 s46, v249, 48
	v_readlane_b32 s47, v249, 49
	v_readlane_b32 s48, v249, 50
	v_readlane_b32 s49, v249, 51
	v_readlane_b32 s50, v249, 52
	v_readlane_b32 s51, v249, 53
	s_cmp_lt_i32 s7, 64
	s_cbranch_scc1 .Lpl3_slow
	s_mov_b64 s[2:3], 0x1000
	global_load_dwordx4 v[52:55], v[28:29], off offset:128
	global_load_dwordx4 v[56:59], v[28:29], off offset:192
	v_lshl_add_u64 v[40:41], v[28:29], 0, s[2:3]
	global_load_dwordx4 v[60:63], v[40:41], off
	global_load_dwordx4 v[64:67], v[40:41], off offset:64
	global_load_dwordx4 v[68:71], v[40:41], off offset:128
	global_load_dwordx4 v[72:75], v[40:41], off offset:192
	v_lshl_add_u64 v[40:41], v[40:41], 0, s[2:3]
	global_load_dwordx4 v[76:79], v[40:41], off
	global_load_dwordx4 v[80:83], v[40:41], off offset:64
	global_load_dwordx4 v[84:87], v[40:41], off offset:128
	global_load_dwordx4 v[88:91], v[40:41], off offset:192
	v_lshl_add_u64 v[40:41], v[40:41], 0, s[2:3]
	global_load_dwordx4 v[92:95], v[40:41], off
	global_load_dwordx4 v[96:99], v[40:41], off offset:64
	global_load_dwordx4 v[100:103], v[40:41], off offset:128
	global_load_dwordx4 v[104:107], v[40:41], off offset:192
	v_lshl_add_u64 v[40:41], v[40:41], 0, s[2:3]
	global_load_dwordx4 v[108:111], v[40:41], off
	global_load_dwordx4 v[112:115], v[40:41], off offset:64
	global_load_dwordx4 v[116:119], v[40:41], off offset:128
	global_load_dwordx4 v[120:123], v[40:41], off offset:192
	v_lshl_add_u64 v[40:41], v[40:41], 0, s[2:3]
	global_load_dwordx4 v[124:127], v[40:41], off
	global_load_dwordx4 v[132:135], v[40:41], off offset:64
	global_load_dwordx4 v[136:139], v[40:41], off offset:128
	global_load_dwordx4 v[140:143], v[40:41], off offset:192
	v_lshl_add_u64 v[40:41], v[40:41], 0, s[2:3]
	global_load_dwordx4 v[144:147], v[40:41], off
	global_load_dwordx4 v[148:151], v[40:41], off offset:64
	global_load_dwordx4 v[152:155], v[40:41], off offset:128
	global_load_dwordx4 v[180:183], v[40:41], off offset:192
	v_lshl_add_u64 v[40:41], v[40:41], 0, s[2:3]
	global_load_dwordx4 v[184:187], v[40:41], off
	global_load_dwordx4 v[188:191], v[40:41], off offset:64
	global_load_dwordx4 v[192:195], v[40:41], off offset:128
	global_load_dwordx4 v[196:199], v[40:41], off offset:192
	v_or_b32_e32 v42, s6, v20
	v_ashrrev_i32_e32 v43, 31, v42
	v_lshl_add_u64 v[42:43], v[42:43], 2, s[42:43]
	global_load_dword v232, v[42:43], off
	global_load_dword v233, v[42:43], off offset:64
	global_load_dword v234, v[42:43], off offset:128
	global_load_dword v235, v[42:43], off offset:192
	global_load_dword v236, v[42:43], off offset:256
	global_load_dword v237, v[42:43], off offset:320
	global_load_dword v238, v[42:43], off offset:384
	global_load_dword v239, v[42:43], off offset:448
	v_add_u32_e32 v44, s17, v21
	v_mov_b32_e32 v45, 0
	v_lshlrev_b64 v[44:45], 10, v[44:45]
	v_lshl_add_u64 v[46:47], s[0:1], 0, v[128:129]
	v_lshl_add_u64 v[46:47], v[46:47], 0, v[44:45]
	global_load_ushort v200, v[46:47], off
	global_load_ushort v201, v[46:47], off offset:1024
	global_load_ushort v202, v[46:47], off offset:2048
	global_load_ushort v203, v[46:47], off offset:3072
	global_load_ushort v204, v[46:47], off offset:32
	global_load_ushort v205, v[46:47], off offset:1056
	global_load_ushort v206, v[46:47], off offset:2080
	global_load_ushort v207, v[46:47], off offset:3104
	global_load_ushort v208, v[46:47], off offset:64
	global_load_ushort v209, v[46:47], off offset:1088
	global_load_ushort v210, v[46:47], off offset:2112
	global_load_ushort v211, v[46:47], off offset:3136
	global_load_ushort v212, v[46:47], off offset:96
	global_load_ushort v213, v[46:47], off offset:1120
	global_load_ushort v214, v[46:47], off offset:2144
	global_load_ushort v215, v[46:47], off offset:3168
	global_load_ushort v216, v[46:47], off offset:128
	global_load_ushort v217, v[46:47], off offset:1152
	global_load_ushort v218, v[46:47], off offset:2176
	global_load_ushort v219, v[46:47], off offset:3200
	global_load_ushort v220, v[46:47], off offset:160
	global_load_ushort v221, v[46:47], off offset:1184
	global_load_ushort v222, v[46:47], off offset:2208
	global_load_ushort v223, v[46:47], off offset:3232
	global_load_ushort v224, v[46:47], off offset:192
	global_load_ushort v225, v[46:47], off offset:1216
	global_load_ushort v226, v[46:47], off offset:2240
	global_load_ushort v227, v[46:47], off offset:3264
	global_load_ushort v228, v[46:47], off offset:224
	global_load_ushort v229, v[46:47], off offset:1248
	global_load_ushort v230, v[46:47], off offset:2272
	global_load_ushort v231, v[46:47], off offset:3296
	s_waitcnt vmcnt(0) lgkmcnt(0)
; #define MFMA16(a, b, c) __builtin_amdgcn_mfma_f32_16x16x32_bf16((a), (b), (c), 0, 0, 0)
; DI float bf2f(bfr b) { return __uint_as_float(((unsigned)b) << 16); }
; DI bfr f2bf(float x) { return (bfr)(pack2(x, 0.f) & 0xFFFFu); }
; DI void pool_item(const Params& p, int layer, int isP, int sq, int tile, int g, char*) {
;     ...
; #pragma unroll
;     for (int nt = 0; nt < 8; ++nt) {
;       const int d = nt * 16 + fr;
;       f32x4 acc = {0.f, 0.f, 0.f, 0.f};
; #pragma unroll
;       for (int ks = 0; ks < 4; ++ks) {
;         bf16x8 bq = *(const bf16x8*)(PwT + d * 128 + ks * 32 + fq * 8);
;         acc = MFMA16(af[ks], bq, acc);
;       }
;       const float scl = p.pool_scale[layer * 512 + ch0 + d];
; #pragma unroll
;       for (int j = 0; j < 4; ++j) {
;         const int t = wid * 16 + fq * 4 + j;
;         if (t0 + t < T) {
;           const long idx = (long)(rowbase + t0 + t) * 512 + ch0 + d;
;           gcy[idx] = f2bf(acc[j] * scl * bf2f(gcy[idx]));
;         }
;       }
;     }
	v_mfma_f32_16x16x32_bf16 v[16:19], v[12:15], v[16:19], 0
	v_mfma_f32_16x16x32_bf16 v[16:19], v[8:11], v[24:27], v[16:19]
	v_mfma_f32_16x16x32_bf16 v[16:19], v[4:7], v[52:55], v[16:19]
	v_mfma_f32_16x16x32_bf16 v[16:19], v[0:3], v[56:59], v[16:19]
	v_mfma_f32_16x16x32_bf16 v[60:63], v[12:15], v[60:63], 0
	v_mfma_f32_16x16x32_bf16 v[60:63], v[8:11], v[64:67], v[60:63]
	v_mfma_f32_16x16x32_bf16 v[60:63], v[4:7], v[68:71], v[60:63]
	v_mfma_f32_16x16x32_bf16 v[60:63], v[0:3], v[72:75], v[60:63]
	v_mfma_f32_16x16x32_bf16 v[76:79], v[12:15], v[76:79], 0
	v_mfma_f32_16x16x32_bf16 v[76:79], v[8:11], v[80:83], v[76:79]
	v_mfma_f32_16x16x32_bf16 v[76:79], v[4:7], v[84:87], v[76:79]
	v_mfma_f32_16x16x32_bf16 v[76:79], v[0:3], v[88:91], v[76:79]
	v_mfma_f32_16x16x32_bf16 v[92:95], v[12:15], v[92:95], 0
	v_mfma_f32_16x16x32_bf16 v[92:95], v[8:11], v[96:99], v[92:95]
	v_mfma_f32_16x16x32_bf16 v[92:95], v[4:7], v[100:103], v[92:95]
	v_mfma_f32_16x16x32_bf16 v[92:95], v[0:3], v[104:107], v[92:95]
	v_mfma_f32_16x16x32_bf16 v[108:111], v[12:15], v[108:111], 0
	v_mfma_f32_16x16x32_bf16 v[108:111], v[8:11], v[112:115], v[108:111]
	v_mfma_f32_16x16x32_bf16 v[108:111], v[4:7], v[116:119], v[108:111]
	v_mfma_f32_16x16x32_bf16 v[108:111], v[0:3], v[120:123], v[108:111]
	v_mfma_f32_16x16x32_bf16 v[124:127], v[12:15], v[124:127], 0
	v_mfma_f32_16x16x32_bf16 v[124:127], v[8:11], v[132:135], v[124:127]
	v_mfma_f32_16x16x32_bf16 v[124:127], v[4:7], v[136:139], v[124:127]
	v_mfma_f32_16x16x32_bf16 v[124:127], v[0:3], v[140:143], v[124:127]
	v_mfma_f32_16x16x32_bf16 v[144:147], v[12:15], v[144:147], 0
	v_mfma_f32_16x16x32_bf16 v[144:147], v[8:11], v[148:151], v[144:147]
	v_mfma_f32_16x16x32_bf16 v[144:147], v[4:7], v[152:155], v[144:147]
	v_mfma_f32_16x16x32_bf16 v[144:147], v[0:3], v[180:183], v[144:147]
	v_mfma_f32_16x16x32_bf16 v[184:187], v[12:15], v[184:187], 0
	v_mfma_f32_16x16x32_bf16 v[184:187], v[8:11], v[188:191], v[184:187]
	v_mfma_f32_16x16x32_bf16 v[184:187], v[4:7], v[192:195], v[184:187]
	v_mfma_f32_16x16x32_bf16 v[184:187], v[0:3], v[196:199], v[184:187]
	s_nop 7
	v_mul_f32_e32 v16, v232, v16
	v_lshlrev_b32_e32 v200, 16, v200
	v_mul_f32_e32 v16, v16, v200
	v_cvt_pk_bf16_f32 v16, v16, v16
	global_store_short v[46:47], v16, off
	v_mul_f32_e32 v17, v232, v17
	v_lshlrev_b32_e32 v201, 16, v201
	v_mul_f32_e32 v17, v17, v201
	v_cvt_pk_bf16_f32 v17, v17, v17
	global_store_short v[46:47], v17, off offset:1024
	v_mul_f32_e32 v18, v232, v18
	v_lshlrev_b32_e32 v202, 16, v202
	v_mul_f32_e32 v18, v18, v202
	v_cvt_pk_bf16_f32 v18, v18, v18
	global_store_short v[46:47], v18, off offset:2048
	v_mul_f32_e32 v19, v232, v19
	v_lshlrev_b32_e32 v203, 16, v203
	v_mul_f32_e32 v19, v19, v203
	v_cvt_pk_bf16_f32 v19, v19, v19
	global_store_short v[46:47], v19, off offset:3072
	v_mul_f32_e32 v60, v233, v60
	v_lshlrev_b32_e32 v204, 16, v204
	v_mul_f32_e32 v60, v60, v204
	v_cvt_pk_bf16_f32 v60, v60, v60
	global_store_short v[46:47], v60, off offset:32
	v_mul_f32_e32 v61, v233, v61
	v_lshlrev_b32_e32 v205, 16, v205
	v_mul_f32_e32 v61, v61, v205
	v_cvt_pk_bf16_f32 v61, v61, v61
	global_store_short v[46:47], v61, off offset:1056
	v_mul_f32_e32 v62, v233, v62
	v_lshlrev_b32_e32 v206, 16, v206
	v_mul_f32_e32 v62, v62, v206
	v_cvt_pk_bf16_f32 v62, v62, v62
	global_store_short v[46:47], v62, off offset:2080
	v_mul_f32_e32 v63, v233, v63
	v_lshlrev_b32_e32 v207, 16, v207
	v_mul_f32_e32 v63, v63, v207
	v_cvt_pk_bf16_f32 v63, v63, v63
	global_store_short v[46:47], v63, off offset:3104
	v_mul_f32_e32 v76, v234, v76
	v_lshlrev_b32_e32 v208, 16, v208
	v_mul_f32_e32 v76, v76, v208
	v_cvt_pk_bf16_f32 v76, v76, v76
	global_store_short v[46:47], v76, off offset:64
	v_mul_f32_e32 v77, v234, v77
	v_lshlrev_b32_e32 v209, 16, v209
	v_mul_f32_e32 v77, v77, v209
	v_cvt_pk_bf16_f32 v77, v77, v77
	global_store_short v[46:47], v77, off offset:1088
	v_mul_f32_e32 v78, v234, v78
	v_lshlrev_b32_e32 v210, 16, v210
	v_mul_f32_e32 v78, v78, v210
	v_cvt_pk_bf16_f32 v78, v78, v78
	global_store_short v[46:47], v78, off offset:2112
	v_mul_f32_e32 v79, v234, v79
	v_lshlrev_b32_e32 v211, 16, v211
	v_mul_f32_e32 v79, v79, v211
	v_cvt_pk_bf16_f32 v79, v79, v79
	global_store_short v[46:47], v79, off offset:3136
	v_mul_f32_e32 v92, v235, v92
	v_lshlrev_b32_e32 v212, 16, v212
	v_mul_f32_e32 v92, v92, v212
	v_cvt_pk_bf16_f32 v92, v92, v92
	global_store_short v[46:47], v92, off offset:96
	v_mul_f32_e32 v93, v235, v93
	v_lshlrev_b32_e32 v213, 16, v213
	v_mul_f32_e32 v93, v93, v213
	v_cvt_pk_bf16_f32 v93, v93, v93
; #define MFMA16(a, b, c) __builtin_amdgcn_mfma_f32_16x16x32_bf16((a), (b), (c), 0, 0, 0)
; DI float bf2f(bfr b) { return __uint_as_float(((unsigned)b) << 16); }
; DI bfr f2bf(float x) { return (bfr)(pack2(x, 0.f) & 0xFFFFu); }
; DI void pool_item(const Params& p, int layer, int isP, int sq, int tile, int g, char*) {
;     ...
;     for (int nt = 0; nt < 8; ++nt) {
;       const int d = nt * 16 + fr;
;       f32x4 acc = {0.f, 0.f, 0.f, 0.f};
; #pragma unroll
;       for (int ks = 0; ks < 4; ++ks) {
;         bf16x8 bq = *(const bf16x8*)(PwT + d * 128 + ks * 32 + fq * 8);
;         acc = MFMA16(af[ks], bq, acc);
;       }
;       const float scl = p.pool_scale[layer * 512 + ch0 + d];
; #pragma unroll
;       for (int j = 0; j < 4; ++j) {
;         const int t = wid * 16 + fq * 4 + j;
;         if (t0 + t < T) {
;           const long idx = (long)(rowbase + t0 + t) * 512 + ch0 + d;
;           gcy[idx] = f2bf(acc[j] * scl * bf2f(gcy[idx]));
;         }
;       }
	global_store_short v[46:47], v93, off offset:1120
	v_mul_f32_e32 v94, v235, v94
	v_lshlrev_b32_e32 v214, 16, v214
	v_mul_f32_e32 v94, v94, v214
	v_cvt_pk_bf16_f32 v94, v94, v94
	global_store_short v[46:47], v94, off offset:2144
	v_mul_f32_e32 v95, v235, v95
	v_lshlrev_b32_e32 v215, 16, v215
	v_mul_f32_e32 v95, v95, v215
	v_cvt_pk_bf16_f32 v95, v95, v95
	global_store_short v[46:47], v95, off offset:3168
	v_mul_f32_e32 v108, v236, v108
	v_lshlrev_b32_e32 v216, 16, v216
	v_mul_f32_e32 v108, v108, v216
	v_cvt_pk_bf16_f32 v108, v108, v108
	global_store_short v[46:47], v108, off offset:128
	v_mul_f32_e32 v109, v236, v109
	v_lshlrev_b32_e32 v217, 16, v217
	v_mul_f32_e32 v109, v109, v217
	v_cvt_pk_bf16_f32 v109, v109, v109
	global_store_short v[46:47], v109, off offset:1152
	v_mul_f32_e32 v110, v236, v110
	v_lshlrev_b32_e32 v218, 16, v218
	v_mul_f32_e32 v110, v110, v218
	v_cvt_pk_bf16_f32 v110, v110, v110
	global_store_short v[46:47], v110, off offset:2176
	v_mul_f32_e32 v111, v236, v111
	v_lshlrev_b32_e32 v219, 16, v219
	v_mul_f32_e32 v111, v111, v219
	v_cvt_pk_bf16_f32 v111, v111, v111
	global_store_short v[46:47], v111, off offset:3200
	v_mul_f32_e32 v124, v237, v124
	v_lshlrev_b32_e32 v220, 16, v220
	v_mul_f32_e32 v124, v124, v220
	v_cvt_pk_bf16_f32 v124, v124, v124
	global_store_short v[46:47], v124, off offset:160
	v_mul_f32_e32 v125, v237, v125
	v_lshlrev_b32_e32 v221, 16, v221
	v_mul_f32_e32 v125, v125, v221
	v_cvt_pk_bf16_f32 v125, v125, v125
	global_store_short v[46:47], v125, off offset:1184
	v_mul_f32_e32 v126, v237, v126
	v_lshlrev_b32_e32 v222, 16, v222
	v_mul_f32_e32 v126, v126, v222
	v_cvt_pk_bf16_f32 v126, v126, v126
	global_store_short v[46:47], v126, off offset:2208
	v_mul_f32_e32 v127, v237, v127
	v_lshlrev_b32_e32 v223, 16, v223
	v_mul_f32_e32 v127, v127, v223
	v_cvt_pk_bf16_f32 v127, v127, v127
	global_store_short v[46:47], v127, off offset:3232
	v_mul_f32_e32 v144, v238, v144
	v_lshlrev_b32_e32 v224, 16, v224
	v_mul_f32_e32 v144, v144, v224
	v_cvt_pk_bf16_f32 v144, v144, v144
	global_store_short v[46:47], v144, off offset:192
	v_mul_f32_e32 v145, v238, v145
	v_lshlrev_b32_e32 v225, 16, v225
	v_mul_f32_e32 v145, v145, v225
	v_cvt_pk_bf16_f32 v145, v145, v145
	global_store_short v[46:47], v145, off offset:1216
	v_mul_f32_e32 v146, v238, v146
	v_lshlrev_b32_e32 v226, 16, v226
	v_mul_f32_e32 v146, v146, v226
	v_cvt_pk_bf16_f32 v146, v146, v146
	global_store_short v[46:47], v146, off offset:2240
	v_mul_f32_e32 v147, v238, v147
	v_lshlrev_b32_e32 v227, 16, v227
	v_mul_f32_e32 v147, v147, v227
	v_cvt_pk_bf16_f32 v147, v147, v147
	global_store_short v[46:47], v147, off offset:3264
	v_mul_f32_e32 v184, v239, v184
	v_lshlrev_b32_e32 v228, 16, v228
	v_mul_f32_e32 v184, v184, v228
	v_cvt_pk_bf16_f32 v184, v184, v184
	global_store_short v[46:47], v184, off offset:224
	v_mul_f32_e32 v185, v239, v185
	v_lshlrev_b32_e32 v229, 16, v229
	v_mul_f32_e32 v185, v185, v229
	v_cvt_pk_bf16_f32 v185, v185, v185
	global_store_short v[46:47], v185, off offset:1248
	v_mul_f32_e32 v186, v239, v186
	v_lshlrev_b32_e32 v230, 16, v230
	v_mul_f32_e32 v186, v186, v230
	v_cvt_pk_bf16_f32 v186, v186, v186
	global_store_short v[46:47], v186, off offset:2272
	v_mul_f32_e32 v187, v239, v187
	v_lshlrev_b32_e32 v231, 16, v231
	v_mul_f32_e32 v187, v187, v231
	v_cvt_pk_bf16_f32 v187, v187, v187
	global_store_short v[46:47], v187, off offset:3296
	s_branch .LBB0_2623
.Lpl3_slow:
	s_waitcnt vmcnt(1) lgkmcnt(3)
	v_mfma_f32_16x16x32_bf16 v[16:19], v[12:15], v[16:19], 0
	s_waitcnt vmcnt(0) lgkmcnt(2)
	v_mfma_f32_16x16x32_bf16 v[16:19], v[8:11], v[24:27], v[16:19]
	global_load_dwordx4 v[24:27], v[28:29], off offset:128
	s_waitcnt vmcnt(0) lgkmcnt(1)
	v_mfma_f32_16x16x32_bf16 v[16:19], v[4:7], v[24:27], v[16:19]
	global_load_dwordx4 v[24:27], v[28:29], off offset:192
	s_waitcnt vmcnt(0) lgkmcnt(0)
	v_mfma_f32_16x16x32_bf16 v[16:19], v[0:3], v[24:27], v[16:19]
	v_or_b32_e32 v24, s6, v20
	v_ashrrev_i32_e32 v25, 31, v24
	v_lshl_add_u64 v[24:25], v[24:25], 2, s[42:43]
	global_load_dword v34, v[24:25], off
	v_add_u32_e32 v26, s17, v21
	v_lshl_add_u64 v[24:25], s[0:1], 0, v[128:129]
	v_ashrrev_i32_e32 v27, 31, v26
	s_and_saveexec_b64 s[0:1], vcc
	s_cbranch_execz .LBB0_2520
	v_lshlrev_b64 v[28:29], 10, v[26:27]
	v_lshl_add_u64 v[28:29], v[24:25], 0, v[28:29]
	global_load_ushort v30, v[28:29], off
	s_waitcnt vmcnt(1)
	v_mul_f32_e32 v16, v34, v16
	s_waitcnt vmcnt(0)
	v_lshlrev_b32_e32 v30, 16, v30
	v_mul_f32_e32 v16, v16, v30
	v_cvt_pk_bf16_f32 v16, v16, s0
	global_store_short v[28:29], v16, off

; DI float bf2f(bfr b) { return __uint_as_float(((unsigned)b) << 16); }
; DI bfr f2bf(float x) { return (bfr)(pack2(x, 0.f) & 0xFFFFu); }
; DI void pool_item(const Params& p, int layer, int isP, int sq, int tile, int g, char*) {
;     ...
;   {
;     const int c = tid & 127;
; #pragma unroll
;     for (int b8 = 0; b8 < 5; ++b8) {
;       float vv[8];
; #pragma unroll
;       for (int u = 0; u < 8; ++u) {
;         const int rr = (b8 * 8 + u) * 2 + (tid >> 7);
;         const int tt = t0 - 15 + rr;
;         float v = 0.f;
;         if (rr < 79) {
;           if (tt < 0) { if (!isP) v = p.state_pool[((long)(layer * NB_S + sq) * 15 + (15 + tt)) * 512 + ch0 + c]; }
;           else if (tt < T) v = bf2f(xcb[(long)(rowbase + tt) * 512 + ch0 + c]);
;         }
;         vv[u] = v;
;       }
; #pragma unroll
;       for (int u = 0; u < 8; ++u) { const int rr = (b8 * 8 + u) * 2 + (tid >> 7); if (rr < 79) xps[rr * 128 + c] = vv[u]; }
;     }
;     ...
; #pragma unroll
;       for (int j = 0; j < 4; ++j) {
;         const int t = wid * 16 + fq * 4 + j;
;         if (t0 + t < T) {
;           const long idx = (long)(rowbase + t0 + t) * 512 + ch0 + d;
;           gcy[idx] = f2bf(acc[j] * scl * bf2f(gcy[idx]));
;         }
;       }
.LBB0_2529:
	v_lshlrev_b64 v[16:17], 10, v[32:33]
	v_lshl_add_u64 v[16:17], v[24:25], 0, v[16:17]
	global_load_ushort v36, v[16:17], off offset:32
	s_waitcnt vmcnt(1)
	v_mul_f32_e32 v18, v21, v18
	s_waitcnt vmcnt(0)
	v_lshlrev_b32_e32 v36, 16, v36
	v_mul_f32_e32 v18, v18, v36
	v_cvt_pk_bf16_f32 v18, v18, s0
	global_store_short v[16:17], v18, off offset:32
	s_or_b64 exec, exec, s[6:7]
	s_and_saveexec_b64 s[6:7], s[4:5]
	s_cbranch_execnz .LBB0_2573
	s_branch .LBB0_2574
.LBB0_2570:
	s_or_b64 exec, exec, s[6:7]
	s_and_saveexec_b64 s[6:7], s[0:1]
	s_cbranch_execz .LBB0_2528
